# removed the redundant s_waitcnt lgkmcnt(0) between the pre-MFMA barrier and the first MFMA in all GEMM loops
# baseline (speedup 1.0000x reference)
; #define PG8_STAGE(bufoff, gbase, voff) do { _Pragma("unroll") for (int _i = 0; _i < 2; ++_i) \
;         __builtin_amdgcn_global_load_lds((const unsigned*)((const char*)(gbase) + (voff)[_i]), (PG8_LAS unsigned*)(lds + (bufoff) + ldsw + _i * 8192), 16, 0, 0); } while (0)
; #define PG8_STAGE_NT(bufoff, gbase, voff) do { _Pragma("unroll") for (int _i = 0; _i < 2; ++_i) \
;         __builtin_amdgcn_global_load_lds((const unsigned*)((const char*)(gbase) + (voff)[_i]), (PG8_LAS unsigned*)(lds + (bufoff) + ldsw + _i * 8192), 16, 0, PG8_B_AUX); } while (0)
; #define PG8_LDA(dst, b, h) do { _Pragma("unroll") for (int m = 0; m < 4; ++m) _Pragma("unroll") for (int k = 0; k < 2; ++k) dst[m][k] = *(const PG8_LAS bf16x8*)(lds + PG8_SA(b, h) + aoff + m * 2048 + k * 1024); } while (0)
; #define PG8_LDB(dst, b, h) do { _Pragma("unroll") for (int n = 0; n < 2; ++n) _Pragma("unroll") for (int k = 0; k < 2; ++k) dst[n][k] = *(const PG8_LAS bf16x8*)(lds + PG8_SB(b, h) + boff + n * 2048 + k * 1024); } while (0)
; #define PG8_MMA(ai, bj, At, Bt) do { __builtin_amdgcn_s_setprio(1); _Pragma("unroll") for (int m = 0; m < 4; ++m) _Pragma("unroll") for (int n = 0; n < 2; ++n) _Pragma("unroll") for (int k = 0; k < 2; ++k) \
;         acc[ai][bj][m][n] = __builtin_amdgcn_mfma_f32_16x16x32_bf16(Bt[n][k], At[m][k], acc[ai][bj][m][n], 0, 0, 0); __builtin_amdgcn_s_setprio(0); } while (0)
; template <class Epi, class Sched, bool ALIGN_EPI = false, bool SP2 = false>
; __device__ __forceinline__ void gemm_phase(PG8_LAS unsigned char* lds, const Gemm g, const Sched& S, const Epi& E, int wid) {
;     ...
;             const char* a2 = last ? nA : cA + (size_t)(t + 2) * kstep; const char* b2 = last ? nB : cB + (size_t)(t + 2) * kstep;
;             const char* a3 = a2 + kstep; const char* b3 = b2 + kstep;
;             if (last && has_next) S.a_ready(nxt);
;             if constexpr (SP2) {
;             PG8_LDB(B0, 0, 0); PG8_LDB(B1, 0, 1); PG8_SCHED; PG8_LDA(At, 0, 0); PG8_STAGE(PG8_SA(1, 1), a1 + hstepA, voffA);
;             PG8_WAIT_V(8); PG8_WAIT_L(0); PG8_BAR; PG8_MMA(0, 0, At, B0); PG8_MMA(0, 1, At, B1); PG8_BAR; PG8_SCHED;
;             PG8_LDA(At, 0, 1); PG8_STAGE_NT(PG8_SB(0, 0), b2, voffB); PG8_STAGE_NT(PG8_SB(0, 1), b2 + hstepB, voffB); PG8_STAGE(PG8_SA(0, 0), a2, voffA);
;             PG8_WAIT_V(8); PG8_WAIT_L(0); PG8_BAR; PG8_MMA(1, 0, At, B0); PG8_MMA(1, 1, At, B1); PG8_BAR; PG8_SCHED;
.LBB0_233:
	ds_read_b128 v[144:147], v155
	ds_read_b128 v[148:151], v155 offset:1024
	ds_read_b128 v[160:163], v155 offset:2048
	ds_read_b128 v[164:167], v155 offset:3072
	ds_read_b128 v[168:171], v156
	ds_read_b128 v[172:175], v156 offset:1024
	ds_read_b128 v[176:179], v156 offset:2048
	ds_read_b128 v[180:183], v156 offset:3072
	s_add_u32 s4, s48, 0x100
	s_addc_u32 s5, s49, 0
	s_add_u32 s98, s48, 0x80
	s_addc_u32 s99, s49, 0
	s_add_u32 s100, s48, 0x104080
	s_addc_u32 s101, s49, 0
	s_cmp_eq_u32 s66, 60
	s_cselect_b32 s53, s45, s5
	s_cselect_b32 s52, s44, s4
	s_cselect_b32 s51, s47, s65
	s_cselect_b32 s50, s46, s64
	s_add_i32 m0, s23, 0xc000
	ds_read_b128 v[184:187], v157
	ds_read_b128 v[188:191], v157 offset:1024
	ds_read_b128 v[192:195], v157 offset:2048
	ds_read_b128 v[196:199], v157 offset:3072
	ds_read_b128 v[200:203], v157 offset:4096
	ds_read_b128 v[204:207], v157 offset:5120
	ds_read_b128 v[208:211], v157 offset:6144
	ds_read_b128 v[212:215], v157 offset:7168
	global_load_lds_dwordx4 v134, s[100:101]
	s_add_i32 m0, s23, 0xe000
	s_nop 0
	global_load_lds_dwordx4 v130, s[100:101]
	s_mov_b32 m0, s55
	s_nop 0
	global_load_lds_dwordx4 v134, s[98:99]
	s_mov_b32 m0, s56
	s_nop 0
	global_load_lds_dwordx4 v130, s[98:99]
	s_waitcnt vmcnt(8)
	s_waitcnt lgkmcnt(0)
	s_barrier
	v_mfma_f32_16x16x32_bf16 v[112:115], v[144:147], v[184:187], v[112:115]
	v_mfma_f32_16x16x32_bf16 v[108:111], v[160:163], v[184:187], v[108:111]
	v_mfma_f32_16x16x32_bf16 v[104:107], v[144:147], v[192:195], v[104:107]
	v_mfma_f32_16x16x32_bf16 v[100:103], v[160:163], v[192:195], v[100:103]
	v_mfma_f32_16x16x32_bf16 v[92:95], v[144:147], v[200:203], v[92:95]
	v_mfma_f32_16x16x32_bf16 v[84:87], v[160:163], v[200:203], v[84:87]
	v_mfma_f32_16x16x32_bf16 v[76:79], v[144:147], v[208:211], v[76:79]
	v_mfma_f32_16x16x32_bf16 v[68:71], v[160:163], v[208:211], v[68:71]
	v_mfma_f32_16x16x32_bf16 v[112:115], v[148:151], v[188:191], v[112:115]
	v_mfma_f32_16x16x32_bf16 v[108:111], v[164:167], v[188:191], v[108:111]
	v_mfma_f32_16x16x32_bf16 v[104:107], v[148:151], v[196:199], v[104:107]
	v_mfma_f32_16x16x32_bf16 v[100:103], v[164:167], v[196:199], v[100:103]
	v_mfma_f32_16x16x32_bf16 v[92:95], v[148:151], v[204:207], v[92:95]
	v_mfma_f32_16x16x32_bf16 v[84:87], v[164:167], v[204:207], v[84:87]
	v_mfma_f32_16x16x32_bf16 v[76:79], v[148:151], v[212:215], v[76:79]
	v_mfma_f32_16x16x32_bf16 v[68:71], v[164:167], v[212:215], v[68:71]
	v_mfma_f32_16x16x32_bf16 v[124:127], v[168:171], v[184:187], v[124:127]
	v_mfma_f32_16x16x32_bf16 v[120:123], v[176:179], v[184:187], v[120:123]
	v_mfma_f32_16x16x32_bf16 v[116:119], v[168:171], v[192:195], v[116:119]
	v_mfma_f32_16x16x32_bf16 v[96:99], v[176:179], v[192:195], v[96:99]
	v_mfma_f32_16x16x32_bf16 v[88:91], v[168:171], v[200:203], v[88:91]
	v_mfma_f32_16x16x32_bf16 v[80:83], v[176:179], v[200:203], v[80:83]
	v_mfma_f32_16x16x32_bf16 v[72:75], v[168:171], v[208:211], v[72:75]
	v_mfma_f32_16x16x32_bf16 v[64:67], v[176:179], v[208:211], v[64:67]
	v_mfma_f32_16x16x32_bf16 v[124:127], v[172:175], v[188:191], v[124:127]
	v_mfma_f32_16x16x32_bf16 v[120:123], v[180:183], v[188:191], v[120:123]
	v_mfma_f32_16x16x32_bf16 v[116:119], v[172:175], v[196:199], v[116:119]
	v_mfma_f32_16x16x32_bf16 v[96:99], v[180:183], v[196:199], v[96:99]
	v_mfma_f32_16x16x32_bf16 v[88:91], v[172:175], v[204:207], v[88:91]
	v_mfma_f32_16x16x32_bf16 v[80:83], v[180:183], v[204:207], v[80:83]
	v_mfma_f32_16x16x32_bf16 v[72:75], v[172:175], v[212:215], v[72:75]
	v_mfma_f32_16x16x32_bf16 v[64:67], v[180:183], v[212:215], v[64:67]
	s_barrier
	s_add_i32 s48, s58, s17
	s_mov_b32 m0, s48
	ds_read_b128 v[184:187], v157 offset:16384
	ds_read_b128 v[188:191], v157 offset:17408
	ds_read_b128 v[192:195], v157 offset:18432
	ds_read_b128 v[196:199], v157 offset:19456
	ds_read_b128 v[200:203], v157 offset:20480
	ds_read_b128 v[204:207], v157 offset:21504
	ds_read_b128 v[208:211], v157 offset:22528
	ds_read_b128 v[212:215], v157 offset:23552
	global_load_lds_dwordx4 v132, s[50:51]
	s_add_i32 m0, s48, 0x2000
	s_add_u32 s48, s50, 0x104000
	s_addc_u32 s49, s51, 0
	s_add_i32 s67, s59, s17
	global_load_lds_dwordx4 v128, s[50:51]
	s_mov_b32 m0, s67
	s_nop 0
	global_load_lds_dwordx4 v132, s[48:49]
	s_add_i32 m0, s67, 0x2000
	s_nop 0
	global_load_lds_dwordx4 v128, s[48:49]
	s_waitcnt vmcnt(4)
	s_waitcnt lgkmcnt(0)
	s_barrier
	v_mfma_f32_16x16x32_bf16 v[60:63], v[144:147], v[184:187], v[60:63]
	v_mfma_f32_16x16x32_bf16 v[52:55], v[160:163], v[184:187], v[52:55]
	v_mfma_f32_16x16x32_bf16 v[44:47], v[144:147], v[192:195], v[44:47]
	v_mfma_f32_16x16x32_bf16 v[36:39], v[160:163], v[192:195], v[36:39]
	v_mfma_f32_16x16x32_bf16 v[28:31], v[144:147], v[200:203], v[28:31]
	v_mfma_f32_16x16x32_bf16 v[20:23], v[160:163], v[200:203], v[20:23]
	v_mfma_f32_16x16x32_bf16 v[12:15], v[144:147], v[208:211], v[12:15]
	v_mfma_f32_16x16x32_bf16 v[4:7], v[160:163], v[208:211], v[4:7]
	v_mfma_f32_16x16x32_bf16 v[60:63], v[148:151], v[188:191], v[60:63]
	v_mfma_f32_16x16x32_bf16 v[52:55], v[164:167], v[188:191], v[52:55]
	v_mfma_f32_16x16x32_bf16 v[44:47], v[148:151], v[196:199], v[44:47]
	v_mfma_f32_16x16x32_bf16 v[36:39], v[164:167], v[196:199], v[36:39]
	v_mfma_f32_16x16x32_bf16 v[28:31], v[148:151], v[204:207], v[28:31]
	v_mfma_f32_16x16x32_bf16 v[20:23], v[164:167], v[204:207], v[20:23]
	v_mfma_f32_16x16x32_bf16 v[12:15], v[148:151], v[212:215], v[12:15]
	v_mfma_f32_16x16x32_bf16 v[4:7], v[164:167], v[212:215], v[4:7]
	v_mfma_f32_16x16x32_bf16 v[56:59], v[168:171], v[184:187], v[56:59]
	v_mfma_f32_16x16x32_bf16 v[48:51], v[176:179], v[184:187], v[48:51]
	v_mfma_f32_16x16x32_bf16 v[40:43], v[168:171], v[192:195], v[40:43]
	v_mfma_f32_16x16x32_bf16 v[32:35], v[176:179], v[192:195], v[32:35]
	v_mfma_f32_16x16x32_bf16 v[24:27], v[168:171], v[200:203], v[24:27]
	v_mfma_f32_16x16x32_bf16 v[16:19], v[176:179], v[200:203], v[16:19]
	v_mfma_f32_16x16x32_bf16 v[8:11], v[168:171], v[208:211], v[8:11]
	v_mfma_f32_16x16x32_bf16 v[0:3], v[176:179], v[208:211], v[0:3]
	v_mfma_f32_16x16x32_bf16 v[56:59], v[172:175], v[188:191], v[56:59]
	v_mfma_f32_16x16x32_bf16 v[48:51], v[180:183], v[188:191], v[48:51]
	v_mfma_f32_16x16x32_bf16 v[40:43], v[172:175], v[196:199], v[40:43]
	v_mfma_f32_16x16x32_bf16 v[32:35], v[180:183], v[196:199], v[32:35]
	v_mfma_f32_16x16x32_bf16 v[24:27], v[172:175], v[204:207], v[24:27]
	v_mfma_f32_16x16x32_bf16 v[16:19], v[180:183], v[204:207], v[16:19]
	v_mfma_f32_16x16x32_bf16 v[8:11], v[172:175], v[212:215], v[8:11]
	v_mfma_f32_16x16x32_bf16 v[0:3], v[180:183], v[212:215], v[0:3]
	s_barrier
; #define PG8_STAGE(bufoff, gbase, voff) do { _Pragma("unroll") for (int _i = 0; _i < 2; ++_i) \
;         __builtin_amdgcn_global_load_lds((const unsigned*)((const char*)(gbase) + (voff)[_i]), (PG8_LAS unsigned*)(lds + (bufoff) + ldsw + _i * 8192), 16, 0, 0); } while (0)
; template <class Epi, class Sched, bool ALIGN_EPI = false, bool SP2 = false>
; __device__ __forceinline__ void gemm_phase(PG8_LAS unsigned char* lds, const Gemm g, const Sched& S, const Epi& E, int wid) {
;     ...
;             PG8_LDB(B0, 1, 0); PG8_LDB(B1, 1, 1); PG8_SCHED; PG8_LDA(At, 1, 0); PG8_STAGE(PG8_SA(0, 1), a2 + hstepA, voffA);
;             PG8_WAIT_V(8); PG8_WAIT_L(0); PG8_BAR; PG8_MMA(0, 0, At, B0); PG8_MMA(0, 1, At, B1); PG8_BAR; PG8_SCHED;
;             PG8_LDA(At, 1, 1); PG8_STAGE_NT(PG8_SB(1, 0), b3, voffB); PG8_STAGE_NT(PG8_SB(1, 1), b3 + hstepB, voffB); PG8_STAGE(PG8_SA(1, 0), a3, voffA);
;             PG8_WAIT_V(8); PG8_WAIT_L(0); PG8_BAR; PG8_MMA(1, 0, At, B0); PG8_MMA(1, 1, At, B1); PG8_BAR; PG8_SCHED;
;             } else {
;             PG8_LDB(B0, 0, 0); PG8_SCHED; PG8_LDA(At, 0, 0); PG8_STAGE(PG8_SA(1, 1), a1 + hstepA, voffA);
;             PG8_WAIT_L(8); PG8_BAR; PG8_WAIT_L(0); PG8_MMA(0, 0, At, B0); PG8_BAR; PG8_SCHED;
;             PG8_LDB(B1, 0, 1); PG8_STAGE_NT(PG8_SB(0, 0), b2, voffB);
;             PG8_BAR; PG8_WAIT_L(0); PG8_MMA(0, 1, At, B1); PG8_BAR;
;             PG8_LDA(At, 0, 1); PG8_STAGE(PG8_SA(0, 0), a2, voffA);
;             PG8_BAR; PG8_WAIT_L(0); PG8_MMA(1, 0, At, B0); PG8_BAR; PG8_SCHED;
;             PG8_STAGE_NT(PG8_SB(0, 1), b2 + hstepB, voffB);
;             PG8_WAIT_V(6); PG8_BAR; PG8_MMA(1, 1, At, B1); PG8_BAR;
;             PG8_LDB(B0, 1, 0); PG8_SCHED; PG8_LDA(At, 1, 0); PG8_STAGE(PG8_SA(0, 1), a2 + hstepA, voffA);
;             PG8_WAIT_L(8); PG8_BAR; PG8_WAIT_L(0); PG8_MMA(0, 0, At, B0); PG8_BAR; PG8_SCHED;
;             PG8_LDB(B1, 1, 1); PG8_STAGE_NT(PG8_SB(1, 0), b3, voffB);
;             PG8_BAR; PG8_WAIT_L(0); PG8_MMA(0, 1, At, B1); PG8_BAR;
;             PG8_LDA(At, 1, 1); PG8_STAGE(PG8_SA(1, 0), a3, voffA);
;             PG8_BAR; PG8_WAIT_L(0); PG8_MMA(1, 0, At, B0); PG8_BAR; PG8_SCHED;
;             PG8_STAGE_NT(PG8_SB(1, 1), b3 + hstepB, voffB);
;             PG8_WAIT_V(6); PG8_BAR; PG8_MMA(1, 1, At, B1); PG8_BAR;
;             }
;         }
;         if constexpr (ALIGN_EPI) { if (wr == 0) PG8_BAR; }
	s_add_i32 s67, 0, 0x18000
	v_add_u32_e32 v159, s67, v153
	s_add_i32 s68, 0, 0x1c000
	ds_read_b128 v[144:147], v159
	ds_read_b128 v[148:151], v159 offset:1024
	ds_read_b128 v[160:163], v159 offset:2048
	ds_read_b128 v[164:167], v159 offset:3072
	v_add_u32_e32 v159, s68, v153
	ds_read_b128 v[168:171], v159
	ds_read_b128 v[172:175], v159 offset:1024
	ds_read_b128 v[176:179], v159 offset:2048
	ds_read_b128 v[180:183], v159 offset:3072
	s_add_u32 s48, s52, 0x104000
	s_addc_u32 s49, s53, 0
	s_mov_b32 m0, s25
	ds_read_b128 v[184:187], v157 offset:32768
	ds_read_b128 v[188:191], v157 offset:33792
	ds_read_b128 v[192:195], v157 offset:34816
	ds_read_b128 v[196:199], v157 offset:35840
	ds_read_b128 v[200:203], v157 offset:36864
	ds_read_b128 v[204:207], v157 offset:37888
	ds_read_b128 v[208:211], v157 offset:38912
	ds_read_b128 v[212:215], v157 offset:39936
	global_load_lds_dwordx4 v134, s[48:49]
	s_mov_b32 m0, s29
	s_nop 0
	global_load_lds_dwordx4 v130, s[48:49]
	s_mov_b32 m0, s23
	s_nop 0
	global_load_lds_dwordx4 v134, s[52:53]
	s_mov_b32 m0, s24
	s_nop 0
	global_load_lds_dwordx4 v130, s[52:53]
	s_waitcnt vmcnt(8)
	s_waitcnt lgkmcnt(0)
	s_barrier
	v_mfma_f32_16x16x32_bf16 v[112:115], v[144:147], v[184:187], v[112:115]
	v_mfma_f32_16x16x32_bf16 v[108:111], v[160:163], v[184:187], v[108:111]
	v_mfma_f32_16x16x32_bf16 v[104:107], v[144:147], v[192:195], v[104:107]
	v_mfma_f32_16x16x32_bf16 v[100:103], v[160:163], v[192:195], v[100:103]
	v_mfma_f32_16x16x32_bf16 v[92:95], v[144:147], v[200:203], v[92:95]
	v_mfma_f32_16x16x32_bf16 v[84:87], v[160:163], v[200:203], v[84:87]
	v_mfma_f32_16x16x32_bf16 v[76:79], v[144:147], v[208:211], v[76:79]
	v_mfma_f32_16x16x32_bf16 v[68:71], v[160:163], v[208:211], v[68:71]
	v_mfma_f32_16x16x32_bf16 v[112:115], v[148:151], v[188:191], v[112:115]
	v_mfma_f32_16x16x32_bf16 v[108:111], v[164:167], v[188:191], v[108:111]
	v_mfma_f32_16x16x32_bf16 v[104:107], v[148:151], v[196:199], v[104:107]
	v_mfma_f32_16x16x32_bf16 v[100:103], v[164:167], v[196:199], v[100:103]
	v_mfma_f32_16x16x32_bf16 v[92:95], v[148:151], v[204:207], v[92:95]
	v_mfma_f32_16x16x32_bf16 v[84:87], v[164:167], v[204:207], v[84:87]
	v_mfma_f32_16x16x32_bf16 v[76:79], v[148:151], v[212:215], v[76:79]
	v_mfma_f32_16x16x32_bf16 v[68:71], v[164:167], v[212:215], v[68:71]
	v_mfma_f32_16x16x32_bf16 v[124:127], v[168:171], v[184:187], v[124:127]
	v_mfma_f32_16x16x32_bf16 v[120:123], v[176:179], v[184:187], v[120:123]
	v_mfma_f32_16x16x32_bf16 v[116:119], v[168:171], v[192:195], v[116:119]
	v_mfma_f32_16x16x32_bf16 v[96:99], v[176:179], v[192:195], v[96:99]
	v_mfma_f32_16x16x32_bf16 v[88:91], v[168:171], v[200:203], v[88:91]
	v_mfma_f32_16x16x32_bf16 v[80:83], v[176:179], v[200:203], v[80:83]
	v_mfma_f32_16x16x32_bf16 v[72:75], v[168:171], v[208:211], v[72:75]
	v_mfma_f32_16x16x32_bf16 v[64:67], v[176:179], v[208:211], v[64:67]
	v_mfma_f32_16x16x32_bf16 v[124:127], v[172:175], v[188:191], v[124:127]
	v_mfma_f32_16x16x32_bf16 v[120:123], v[180:183], v[188:191], v[120:123]
	v_mfma_f32_16x16x32_bf16 v[116:119], v[172:175], v[196:199], v[116:119]
	v_mfma_f32_16x16x32_bf16 v[96:99], v[180:183], v[196:199], v[96:99]
	v_mfma_f32_16x16x32_bf16 v[88:91], v[172:175], v[204:207], v[88:91]
	v_mfma_f32_16x16x32_bf16 v[80:83], v[180:183], v[204:207], v[80:83]
	v_mfma_f32_16x16x32_bf16 v[72:75], v[172:175], v[212:215], v[72:75]
	v_mfma_f32_16x16x32_bf16 v[64:67], v[180:183], v[212:215], v[64:67]
	s_barrier
	s_add_i32 s48, s67, s17
	s_mov_b32 m0, s48
	s_add_u32 s98, s50, 0x80
	s_addc_u32 s99, s51, 0
	ds_read_b128 v[184:187], v157 offset:49152
	ds_read_b128 v[188:191], v157 offset:50176
	ds_read_b128 v[192:195], v157 offset:51200
	ds_read_b128 v[196:199], v157 offset:52224
	ds_read_b128 v[200:203], v157 offset:53248
	ds_read_b128 v[204:207], v157 offset:54272
	ds_read_b128 v[208:211], v157 offset:55296
	ds_read_b128 v[212:215], v157 offset:56320
	global_load_lds_dwordx4 v132, s[98:99]
	s_add_i32 m0, s48, 0x2000
	s_add_u32 s48, s50, 0x104080
	s_addc_u32 s49, s51, 0
	s_add_i32 s50, s68, s17
	global_load_lds_dwordx4 v128, s[98:99]
	s_mov_b32 m0, s50
	s_nop 0
	global_load_lds_dwordx4 v132, s[48:49]
	s_add_i32 m0, s50, 0x2000
	s_nop 0
	global_load_lds_dwordx4 v128, s[48:49]
	s_waitcnt vmcnt(4)
	s_waitcnt lgkmcnt(0)
	s_barrier
	v_mfma_f32_16x16x32_bf16 v[60:63], v[144:147], v[184:187], v[60:63]
	v_mfma_f32_16x16x32_bf16 v[52:55], v[160:163], v[184:187], v[52:55]
	v_mfma_f32_16x16x32_bf16 v[44:47], v[144:147], v[192:195], v[44:47]
	v_mfma_f32_16x16x32_bf16 v[36:39], v[160:163], v[192:195], v[36:39]
	v_mfma_f32_16x16x32_bf16 v[28:31], v[144:147], v[200:203], v[28:31]
	v_mfma_f32_16x16x32_bf16 v[20:23], v[160:163], v[200:203], v[20:23]
	v_mfma_f32_16x16x32_bf16 v[12:15], v[144:147], v[208:211], v[12:15]
	v_mfma_f32_16x16x32_bf16 v[4:7], v[160:163], v[208:211], v[4:7]
	v_mfma_f32_16x16x32_bf16 v[60:63], v[148:151], v[188:191], v[60:63]
	v_mfma_f32_16x16x32_bf16 v[52:55], v[164:167], v[188:191], v[52:55]
	v_mfma_f32_16x16x32_bf16 v[44:47], v[148:151], v[196:199], v[44:47]
	v_mfma_f32_16x16x32_bf16 v[36:39], v[164:167], v[196:199], v[36:39]
	v_mfma_f32_16x16x32_bf16 v[28:31], v[148:151], v[204:207], v[28:31]
	v_mfma_f32_16x16x32_bf16 v[20:23], v[164:167], v[204:207], v[20:23]
	v_mfma_f32_16x16x32_bf16 v[12:15], v[148:151], v[212:215], v[12:15]
	v_mfma_f32_16x16x32_bf16 v[4:7], v[164:167], v[212:215], v[4:7]
	v_mfma_f32_16x16x32_bf16 v[56:59], v[168:171], v[184:187], v[56:59]
	v_mfma_f32_16x16x32_bf16 v[48:51], v[176:179], v[184:187], v[48:51]
	v_mfma_f32_16x16x32_bf16 v[40:43], v[168:171], v[192:195], v[40:43]
	v_mfma_f32_16x16x32_bf16 v[32:35], v[176:179], v[192:195], v[32:35]
	v_mfma_f32_16x16x32_bf16 v[24:27], v[168:171], v[200:203], v[24:27]
	v_mfma_f32_16x16x32_bf16 v[16:19], v[176:179], v[200:203], v[16:19]
	v_mfma_f32_16x16x32_bf16 v[8:11], v[168:171], v[208:211], v[8:11]
	v_mfma_f32_16x16x32_bf16 v[0:3], v[176:179], v[208:211], v[0:3]
	v_mfma_f32_16x16x32_bf16 v[56:59], v[172:175], v[188:191], v[56:59]
	v_mfma_f32_16x16x32_bf16 v[48:51], v[180:183], v[188:191], v[48:51]
	v_mfma_f32_16x16x32_bf16 v[40:43], v[172:175], v[196:199], v[40:43]
	v_mfma_f32_16x16x32_bf16 v[32:35], v[180:183], v[196:199], v[32:35]
	v_mfma_f32_16x16x32_bf16 v[24:27], v[172:175], v[204:207], v[24:27]
	v_mfma_f32_16x16x32_bf16 v[16:19], v[180:183], v[204:207], v[16:19]
	v_mfma_f32_16x16x32_bf16 v[8:11], v[172:175], v[212:215], v[8:11]
	v_mfma_f32_16x16x32_bf16 v[0:3], v[180:183], v[212:215], v[0:3]
	s_barrier
	s_add_i32 s66, s66, 2
	s_add_u32 s64, s64, 0x100
	s_addc_u32 s65, s65, 0
	s_cmp_gt_u32 s66, 61
	s_mov_b64 s[48:49], s[4:5]
	s_cbranch_scc0 .LBB0_233
	s_and_b64 vcc, exec, s[42:43]
	s_cbranch_vccz .LBB0_236
	s_barrier

; #define PG8_STAGE(bufoff, gbase, voff) do { _Pragma("unroll") for (int _i = 0; _i < 2; ++_i) \
;         __builtin_amdgcn_global_load_lds((const unsigned*)((const char*)(gbase) + (voff)[_i]), (PG8_LAS unsigned*)(lds + (bufoff) + ldsw + _i * 8192), 16, 0, 0); } while (0)
; #define PG8_STAGE_NT(bufoff, gbase, voff) do { _Pragma("unroll") for (int _i = 0; _i < 2; ++_i) \
;         __builtin_amdgcn_global_load_lds((const unsigned*)((const char*)(gbase) + (voff)[_i]), (PG8_LAS unsigned*)(lds + (bufoff) + ldsw + _i * 8192), 16, 0, PG8_B_AUX); } while (0)
; #define PG8_LDA(dst, b, h) do { _Pragma("unroll") for (int m = 0; m < 4; ++m) _Pragma("unroll") for (int k = 0; k < 2; ++k) dst[m][k] = *(const PG8_LAS bf16x8*)(lds + PG8_SA(b, h) + aoff + m * 2048 + k * 1024); } while (0)
; #define PG8_LDB(dst, b, h) do { _Pragma("unroll") for (int n = 0; n < 2; ++n) _Pragma("unroll") for (int k = 0; k < 2; ++k) dst[n][k] = *(const PG8_LAS bf16x8*)(lds + PG8_SB(b, h) + boff + n * 2048 + k * 1024); } while (0)
; #define PG8_WAIT_V(n) asm volatile("s_waitcnt vmcnt(" #n ")" ::: "memory")
; #define PG8_WAIT_L(n) asm volatile("s_waitcnt lgkmcnt(" #n ")" ::: "memory")
; #define PG8_BAR __builtin_amdgcn_s_barrier()
; #define PG8_SCHED __builtin_amdgcn_sched_barrier(0)
; template <class Epi, class Sched, bool ALIGN_EPI = false, bool SP2 = false>
; __device__ __forceinline__ void gemm_phase(PG8_LAS unsigned char* lds, const Gemm g, const Sched& S, const Epi& E, int wid) {
;     ...
;             const bool last = (t == nt - 2);
;             const char* a1 = cA + (size_t)(t + 1) * kstep;
;             const char* a2 = last ? nA : cA + (size_t)(t + 2) * kstep; const char* b2 = last ? nB : cB + (size_t)(t + 2) * kstep;
;             const char* a3 = a2 + kstep; const char* b3 = b2 + kstep;
;             if (last && has_next) S.a_ready(nxt);
;             if constexpr (SP2) {
;             PG8_LDB(B0, 0, 0); PG8_LDB(B1, 0, 1); PG8_SCHED; PG8_LDA(At, 0, 0); PG8_STAGE(PG8_SA(1, 1), a1 + hstepA, voffA);
;             PG8_WAIT_V(8); PG8_WAIT_L(0); PG8_BAR; PG8_MMA(0, 0, At, B0); PG8_MMA(0, 1, At, B1); PG8_BAR; PG8_SCHED;
;             PG8_LDA(At, 0, 1); PG8_STAGE_NT(PG8_SB(0, 0), b2, voffB); PG8_STAGE_NT(PG8_SB(0, 1), b2 + hstepB, voffB); PG8_STAGE(PG8_SA(0, 0), a2, voffA);
;             PG8_WAIT_V(8); PG8_WAIT_L(0); PG8_BAR; PG8_MMA(1, 0, At, B0); PG8_MMA(1, 1, At, B1); PG8_BAR; PG8_SCHED;
.LBB0_317:
	ds_read_b128 v[128:131], v205
	ds_read_b128 v[132:135], v205 offset:1024
	ds_read_b128 v[136:139], v205 offset:2048
	ds_read_b128 v[140:143], v205 offset:3072
	ds_read_b128 v[144:147], v206
	ds_read_b128 v[148:151], v206 offset:1024
	ds_read_b128 v[152:155], v206 offset:2048
	ds_read_b128 v[156:159], v206 offset:3072
	s_add_u32 s48, s46, 0x100
	s_addc_u32 s49, s47, 0
	s_add_u32 s98, s46, 0x80
	s_addc_u32 s99, s47, 0
	s_add_u32 s100, s46, 0x2b4080
	s_addc_u32 s101, s47, 0
	s_cmpk_eq_i32 s64, 0xa8
	s_cselect_b32 s53, s7, s49
	s_cselect_b32 s52, s6, s48
	s_cselect_b32 s51, s45, s63
	s_cselect_b32 s50, s44, s62
	s_add_i32 m0, s19, 0xc000
	ds_read_b128 v[160:163], v207
	ds_read_b128 v[164:167], v207 offset:1024
	ds_read_b128 v[184:187], v207 offset:2048
	ds_read_b128 v[188:191], v207 offset:3072
	ds_read_b128 v[192:195], v207 offset:4096
	ds_read_b128 v[196:199], v207 offset:5120
	ds_read_b128 v[210:213], v207 offset:6144
	ds_read_b128 v[214:217], v207 offset:7168
	global_load_lds_dwordx4 v168, s[100:101]
	s_add_i32 m0, s19, 0xe000
	s_nop 0
	global_load_lds_dwordx4 v172, s[100:101]
	s_mov_b32 m0, s29
	s_nop 0
	global_load_lds_dwordx4 v168, s[98:99]
	s_mov_b32 m0, s54
	s_nop 0
	global_load_lds_dwordx4 v172, s[98:99]
	s_waitcnt vmcnt(8)
	s_waitcnt lgkmcnt(0)
	s_barrier
	v_mfma_f32_16x16x32_bf16 v[124:127], v[128:131], v[160:163], v[124:127]
	v_mfma_f32_16x16x32_bf16 v[120:123], v[136:139], v[160:163], v[120:123]
	v_mfma_f32_16x16x32_bf16 v[116:119], v[128:131], v[184:187], v[116:119]
	v_mfma_f32_16x16x32_bf16 v[112:115], v[136:139], v[184:187], v[112:115]
	v_mfma_f32_16x16x32_bf16 v[92:95], v[128:131], v[192:195], v[92:95]
	v_mfma_f32_16x16x32_bf16 v[88:91], v[136:139], v[192:195], v[88:91]
	v_mfma_f32_16x16x32_bf16 v[76:79], v[128:131], v[210:213], v[76:79]
	v_mfma_f32_16x16x32_bf16 v[72:75], v[136:139], v[210:213], v[72:75]
	v_mfma_f32_16x16x32_bf16 v[124:127], v[132:135], v[164:167], v[124:127]
	v_mfma_f32_16x16x32_bf16 v[120:123], v[140:143], v[164:167], v[120:123]
	v_mfma_f32_16x16x32_bf16 v[116:119], v[132:135], v[188:191], v[116:119]
	v_mfma_f32_16x16x32_bf16 v[112:115], v[140:143], v[188:191], v[112:115]
	v_mfma_f32_16x16x32_bf16 v[92:95], v[132:135], v[196:199], v[92:95]
	v_mfma_f32_16x16x32_bf16 v[88:91], v[140:143], v[196:199], v[88:91]
	v_mfma_f32_16x16x32_bf16 v[76:79], v[132:135], v[214:217], v[76:79]
	v_mfma_f32_16x16x32_bf16 v[72:75], v[140:143], v[214:217], v[72:75]
	v_mfma_f32_16x16x32_bf16 v[108:111], v[144:147], v[160:163], v[108:111]
	v_mfma_f32_16x16x32_bf16 v[104:107], v[152:155], v[160:163], v[104:107]
	v_mfma_f32_16x16x32_bf16 v[100:103], v[144:147], v[184:187], v[100:103]
	v_mfma_f32_16x16x32_bf16 v[96:99], v[152:155], v[184:187], v[96:99]
	v_mfma_f32_16x16x32_bf16 v[84:87], v[144:147], v[192:195], v[84:87]
	v_mfma_f32_16x16x32_bf16 v[80:83], v[152:155], v[192:195], v[80:83]
	v_mfma_f32_16x16x32_bf16 v[68:71], v[144:147], v[210:213], v[68:71]
	v_mfma_f32_16x16x32_bf16 v[64:67], v[152:155], v[210:213], v[64:67]
	v_mfma_f32_16x16x32_bf16 v[108:111], v[148:151], v[164:167], v[108:111]
	v_mfma_f32_16x16x32_bf16 v[104:107], v[156:159], v[164:167], v[104:107]
	v_mfma_f32_16x16x32_bf16 v[100:103], v[148:151], v[188:191], v[100:103]
	v_mfma_f32_16x16x32_bf16 v[96:99], v[156:159], v[188:191], v[96:99]
	v_mfma_f32_16x16x32_bf16 v[84:87], v[148:151], v[196:199], v[84:87]
	v_mfma_f32_16x16x32_bf16 v[80:83], v[156:159], v[196:199], v[80:83]
	v_mfma_f32_16x16x32_bf16 v[68:71], v[148:151], v[214:217], v[68:71]
	v_mfma_f32_16x16x32_bf16 v[64:67], v[156:159], v[214:217], v[64:67]
	s_barrier
	s_add_i32 s46, s57, s17
	s_mov_b32 m0, s46
	ds_read_b128 v[160:163], v207 offset:16384
	ds_read_b128 v[164:167], v207 offset:17408
	ds_read_b128 v[184:187], v207 offset:18432
	ds_read_b128 v[188:191], v207 offset:19456
	ds_read_b128 v[192:195], v207 offset:20480
	ds_read_b128 v[196:199], v207 offset:21504
	ds_read_b128 v[210:213], v207 offset:22528
	ds_read_b128 v[214:217], v207 offset:23552
	global_load_lds_dwordx4 v170, s[50:51]
	s_add_i32 m0, s46, 0x2000
	s_add_u32 s46, s50, 0x2b4000
	s_addc_u32 s47, s51, 0
	s_add_i32 s65, s58, s17
	global_load_lds_dwordx4 v174, s[50:51]
	s_mov_b32 m0, s65
	s_nop 0
	global_load_lds_dwordx4 v170, s[46:47]
	s_add_i32 m0, s65, 0x2000
	s_nop 0
	global_load_lds_dwordx4 v174, s[46:47]
	s_waitcnt vmcnt(4)
	s_waitcnt lgkmcnt(0)
	s_barrier
	v_mfma_f32_16x16x32_bf16 v[60:63], v[128:131], v[160:163], v[60:63]
	v_mfma_f32_16x16x32_bf16 v[56:59], v[136:139], v[160:163], v[56:59]
	v_mfma_f32_16x16x32_bf16 v[44:47], v[128:131], v[184:187], v[44:47]
	v_mfma_f32_16x16x32_bf16 v[40:43], v[136:139], v[184:187], v[40:43]
	v_mfma_f32_16x16x32_bf16 v[28:31], v[128:131], v[192:195], v[28:31]
	v_mfma_f32_16x16x32_bf16 v[24:27], v[136:139], v[192:195], v[24:27]
	v_mfma_f32_16x16x32_bf16 v[12:15], v[128:131], v[210:213], v[12:15]
	v_mfma_f32_16x16x32_bf16 v[8:11], v[136:139], v[210:213], v[8:11]
	v_mfma_f32_16x16x32_bf16 v[60:63], v[132:135], v[164:167], v[60:63]
	v_mfma_f32_16x16x32_bf16 v[56:59], v[140:143], v[164:167], v[56:59]
	v_mfma_f32_16x16x32_bf16 v[44:47], v[132:135], v[188:191], v[44:47]
	v_mfma_f32_16x16x32_bf16 v[40:43], v[140:143], v[188:191], v[40:43]
	v_mfma_f32_16x16x32_bf16 v[28:31], v[132:135], v[196:199], v[28:31]
	v_mfma_f32_16x16x32_bf16 v[24:27], v[140:143], v[196:199], v[24:27]
	v_mfma_f32_16x16x32_bf16 v[12:15], v[132:135], v[214:217], v[12:15]
	v_mfma_f32_16x16x32_bf16 v[8:11], v[140:143], v[214:217], v[8:11]
	v_mfma_f32_16x16x32_bf16 v[52:55], v[144:147], v[160:163], v[52:55]
	v_mfma_f32_16x16x32_bf16 v[48:51], v[152:155], v[160:163], v[48:51]
	v_mfma_f32_16x16x32_bf16 v[36:39], v[144:147], v[184:187], v[36:39]
	v_mfma_f32_16x16x32_bf16 v[32:35], v[152:155], v[184:187], v[32:35]
	v_mfma_f32_16x16x32_bf16 v[20:23], v[144:147], v[192:195], v[20:23]
	v_mfma_f32_16x16x32_bf16 v[16:19], v[152:155], v[192:195], v[16:19]
	v_mfma_f32_16x16x32_bf16 v[4:7], v[144:147], v[210:213], v[4:7]
	v_mfma_f32_16x16x32_bf16 v[0:3], v[152:155], v[210:213], v[0:3]
	v_mfma_f32_16x16x32_bf16 v[52:55], v[148:151], v[164:167], v[52:55]
	v_mfma_f32_16x16x32_bf16 v[48:51], v[156:159], v[164:167], v[48:51]
	v_mfma_f32_16x16x32_bf16 v[36:39], v[148:151], v[188:191], v[36:39]
	v_mfma_f32_16x16x32_bf16 v[32:35], v[156:159], v[188:191], v[32:35]
	v_mfma_f32_16x16x32_bf16 v[20:23], v[148:151], v[196:199], v[20:23]
	v_mfma_f32_16x16x32_bf16 v[16:19], v[156:159], v[196:199], v[16:19]
	v_mfma_f32_16x16x32_bf16 v[4:7], v[148:151], v[214:217], v[4:7]
	v_mfma_f32_16x16x32_bf16 v[0:3], v[156:159], v[214:217], v[0:3]
	s_barrier
; #define PG8_STAGE(bufoff, gbase, voff) do { _Pragma("unroll") for (int _i = 0; _i < 2; ++_i) \
;         __builtin_amdgcn_global_load_lds((const unsigned*)((const char*)(gbase) + (voff)[_i]), (PG8_LAS unsigned*)(lds + (bufoff) + ldsw + _i * 8192), 16, 0, 0); } while (0)
; #define PG8_STAGE_NT(bufoff, gbase, voff) do { _Pragma("unroll") for (int _i = 0; _i < 2; ++_i) \
;         __builtin_amdgcn_global_load_lds((const unsigned*)((const char*)(gbase) + (voff)[_i]), (PG8_LAS unsigned*)(lds + (bufoff) + ldsw + _i * 8192), 16, 0, PG8_B_AUX); } while (0)
; #define PG8_LDA(dst, b, h) do { _Pragma("unroll") for (int m = 0; m < 4; ++m) _Pragma("unroll") for (int k = 0; k < 2; ++k) dst[m][k] = *(const PG8_LAS bf16x8*)(lds + PG8_SA(b, h) + aoff + m * 2048 + k * 1024); } while (0)
; #define PG8_LDB(dst, b, h) do { _Pragma("unroll") for (int n = 0; n < 2; ++n) _Pragma("unroll") for (int k = 0; k < 2; ++k) dst[n][k] = *(const PG8_LAS bf16x8*)(lds + PG8_SB(b, h) + boff + n * 2048 + k * 1024); } while (0)
; #define PG8_MMA(ai, bj, At, Bt) do { __builtin_amdgcn_s_setprio(1); _Pragma("unroll") for (int m = 0; m < 4; ++m) _Pragma("unroll") for (int n = 0; n < 2; ++n) _Pragma("unroll") for (int k = 0; k < 2; ++k) \
;         acc[ai][bj][m][n] = __builtin_amdgcn_mfma_f32_16x16x32_bf16(Bt[n][k], At[m][k], acc[ai][bj][m][n], 0, 0, 0); __builtin_amdgcn_s_setprio(0); } while (0)
; #define PG8_WAIT_V(n) asm volatile("s_waitcnt vmcnt(" #n ")" ::: "memory")
; #define PG8_WAIT_L(n) asm volatile("s_waitcnt lgkmcnt(" #n ")" ::: "memory")
; #define PG8_BAR __builtin_amdgcn_s_barrier()
; #define PG8_SCHED __builtin_amdgcn_sched_barrier(0)
; template <class Epi, class Sched, bool ALIGN_EPI = false, bool SP2 = false>
; __device__ __forceinline__ void gemm_phase(PG8_LAS unsigned char* lds, const Gemm g, const Sched& S, const Epi& E, int wid) {
;     ...
;             PG8_LDB(B0, 1, 0); PG8_LDB(B1, 1, 1); PG8_SCHED; PG8_LDA(At, 1, 0); PG8_STAGE(PG8_SA(0, 1), a2 + hstepA, voffA);
;             PG8_WAIT_V(8); PG8_WAIT_L(0); PG8_BAR; PG8_MMA(0, 0, At, B0); PG8_MMA(0, 1, At, B1); PG8_BAR; PG8_SCHED;
;             PG8_LDA(At, 1, 1); PG8_STAGE_NT(PG8_SB(1, 0), b3, voffB); PG8_STAGE_NT(PG8_SB(1, 1), b3 + hstepB, voffB); PG8_STAGE(PG8_SA(1, 0), a3, voffA);
;             PG8_WAIT_V(8); PG8_WAIT_L(0); PG8_BAR; PG8_MMA(1, 0, At, B0); PG8_MMA(1, 1, At, B1); PG8_BAR; PG8_SCHED;
	s_add_i32 s65, 0, 0x18000
	v_add_u32_e32 v140, s65, v203
	s_add_i32 s66, 0, 0x1c000
	ds_read_b128 v[128:131], v140
	ds_read_b128 v[132:135], v140 offset:1024
	ds_read_b128 v[136:139], v140 offset:2048
	ds_read_b128 v[140:143], v140 offset:3072
	v_add_u32_e32 v156, s66, v203
	ds_read_b128 v[144:147], v156
	ds_read_b128 v[148:151], v156 offset:1024
	ds_read_b128 v[152:155], v156 offset:2048
	ds_read_b128 v[156:159], v156 offset:3072
	s_add_u32 s46, s52, 0x2b4000
	s_addc_u32 s47, s53, 0
	s_mov_b32 m0, s23
	ds_read_b128 v[160:163], v207 offset:32768
	ds_read_b128 v[164:167], v207 offset:33792
	ds_read_b128 v[184:187], v207 offset:34816
	ds_read_b128 v[188:191], v207 offset:35840
	ds_read_b128 v[192:195], v207 offset:36864
	ds_read_b128 v[196:199], v207 offset:37888
	ds_read_b128 v[210:213], v207 offset:38912
	ds_read_b128 v[214:217], v207 offset:39936
	global_load_lds_dwordx4 v168, s[46:47]
	s_mov_b32 m0, s24
	s_nop 0
	global_load_lds_dwordx4 v172, s[46:47]
	s_mov_b32 m0, s19
	s_nop 0
	global_load_lds_dwordx4 v168, s[52:53]
	s_mov_b32 m0, s22
	s_nop 0
	global_load_lds_dwordx4 v172, s[52:53]
	s_waitcnt vmcnt(8)
	s_waitcnt lgkmcnt(0)
	s_barrier
	v_mfma_f32_16x16x32_bf16 v[124:127], v[128:131], v[160:163], v[124:127]
	v_mfma_f32_16x16x32_bf16 v[120:123], v[136:139], v[160:163], v[120:123]
	v_mfma_f32_16x16x32_bf16 v[116:119], v[128:131], v[184:187], v[116:119]
	v_mfma_f32_16x16x32_bf16 v[112:115], v[136:139], v[184:187], v[112:115]
	v_mfma_f32_16x16x32_bf16 v[92:95], v[128:131], v[192:195], v[92:95]
	v_mfma_f32_16x16x32_bf16 v[88:91], v[136:139], v[192:195], v[88:91]
	v_mfma_f32_16x16x32_bf16 v[76:79], v[128:131], v[210:213], v[76:79]
	v_mfma_f32_16x16x32_bf16 v[72:75], v[136:139], v[210:213], v[72:75]
	v_mfma_f32_16x16x32_bf16 v[124:127], v[132:135], v[164:167], v[124:127]
	v_mfma_f32_16x16x32_bf16 v[120:123], v[140:143], v[164:167], v[120:123]
	v_mfma_f32_16x16x32_bf16 v[116:119], v[132:135], v[188:191], v[116:119]
	v_mfma_f32_16x16x32_bf16 v[112:115], v[140:143], v[188:191], v[112:115]
	v_mfma_f32_16x16x32_bf16 v[92:95], v[132:135], v[196:199], v[92:95]
	v_mfma_f32_16x16x32_bf16 v[88:91], v[140:143], v[196:199], v[88:91]
	v_mfma_f32_16x16x32_bf16 v[76:79], v[132:135], v[214:217], v[76:79]
	v_mfma_f32_16x16x32_bf16 v[72:75], v[140:143], v[214:217], v[72:75]
	v_mfma_f32_16x16x32_bf16 v[108:111], v[144:147], v[160:163], v[108:111]
	v_mfma_f32_16x16x32_bf16 v[104:107], v[152:155], v[160:163], v[104:107]
	v_mfma_f32_16x16x32_bf16 v[100:103], v[144:147], v[184:187], v[100:103]
	v_mfma_f32_16x16x32_bf16 v[96:99], v[152:155], v[184:187], v[96:99]
	v_mfma_f32_16x16x32_bf16 v[84:87], v[144:147], v[192:195], v[84:87]
	v_mfma_f32_16x16x32_bf16 v[80:83], v[152:155], v[192:195], v[80:83]
	v_mfma_f32_16x16x32_bf16 v[68:71], v[144:147], v[210:213], v[68:71]
	v_mfma_f32_16x16x32_bf16 v[64:67], v[152:155], v[210:213], v[64:67]
	v_mfma_f32_16x16x32_bf16 v[108:111], v[148:151], v[164:167], v[108:111]
	v_mfma_f32_16x16x32_bf16 v[104:107], v[156:159], v[164:167], v[104:107]
	v_mfma_f32_16x16x32_bf16 v[100:103], v[148:151], v[188:191], v[100:103]
	v_mfma_f32_16x16x32_bf16 v[96:99], v[156:159], v[188:191], v[96:99]
	v_mfma_f32_16x16x32_bf16 v[84:87], v[148:151], v[196:199], v[84:87]
	v_mfma_f32_16x16x32_bf16 v[80:83], v[156:159], v[196:199], v[80:83]
	v_mfma_f32_16x16x32_bf16 v[68:71], v[148:151], v[214:217], v[68:71]
	v_mfma_f32_16x16x32_bf16 v[64:67], v[156:159], v[214:217], v[64:67]
	s_barrier
	s_add_i32 s46, s65, s17
	s_mov_b32 m0, s46
	s_add_u32 s98, s50, 0x80
	s_addc_u32 s99, s51, 0
	ds_read_b128 v[160:163], v207 offset:49152
	ds_read_b128 v[164:167], v207 offset:50176
	ds_read_b128 v[184:187], v207 offset:51200
	ds_read_b128 v[188:191], v207 offset:52224
	ds_read_b128 v[192:195], v207 offset:53248
	ds_read_b128 v[196:199], v207 offset:54272
	ds_read_b128 v[210:213], v207 offset:55296
	ds_read_b128 v[214:217], v207 offset:56320
	global_load_lds_dwordx4 v170, s[98:99]
	s_add_i32 m0, s46, 0x2000
	s_add_u32 s46, s50, 0x2b4080
	s_addc_u32 s47, s51, 0
	s_add_i32 s50, s66, s17
	global_load_lds_dwordx4 v174, s[98:99]
	s_mov_b32 m0, s50
	s_nop 0
	global_load_lds_dwordx4 v170, s[46:47]
	s_add_i32 m0, s50, 0x2000
	s_nop 0
	global_load_lds_dwordx4 v174, s[46:47]
	s_waitcnt vmcnt(4)
	s_waitcnt lgkmcnt(0)
	s_barrier
	v_mfma_f32_16x16x32_bf16 v[60:63], v[128:131], v[160:163], v[60:63]
	v_mfma_f32_16x16x32_bf16 v[56:59], v[136:139], v[160:163], v[56:59]
	v_mfma_f32_16x16x32_bf16 v[44:47], v[128:131], v[184:187], v[44:47]
	v_mfma_f32_16x16x32_bf16 v[40:43], v[136:139], v[184:187], v[40:43]
	v_mfma_f32_16x16x32_bf16 v[28:31], v[128:131], v[192:195], v[28:31]
	v_mfma_f32_16x16x32_bf16 v[24:27], v[136:139], v[192:195], v[24:27]
	v_mfma_f32_16x16x32_bf16 v[12:15], v[128:131], v[210:213], v[12:15]
	v_mfma_f32_16x16x32_bf16 v[8:11], v[136:139], v[210:213], v[8:11]
	v_mfma_f32_16x16x32_bf16 v[60:63], v[132:135], v[164:167], v[60:63]
	v_mfma_f32_16x16x32_bf16 v[56:59], v[140:143], v[164:167], v[56:59]
	v_mfma_f32_16x16x32_bf16 v[44:47], v[132:135], v[188:191], v[44:47]
	v_mfma_f32_16x16x32_bf16 v[40:43], v[140:143], v[188:191], v[40:43]
	v_mfma_f32_16x16x32_bf16 v[28:31], v[132:135], v[196:199], v[28:31]
	v_mfma_f32_16x16x32_bf16 v[24:27], v[140:143], v[196:199], v[24:27]
	v_mfma_f32_16x16x32_bf16 v[12:15], v[132:135], v[214:217], v[12:15]
	v_mfma_f32_16x16x32_bf16 v[8:11], v[140:143], v[214:217], v[8:11]
	v_mfma_f32_16x16x32_bf16 v[52:55], v[144:147], v[160:163], v[52:55]
	v_mfma_f32_16x16x32_bf16 v[48:51], v[152:155], v[160:163], v[48:51]
	v_mfma_f32_16x16x32_bf16 v[36:39], v[144:147], v[184:187], v[36:39]
	v_mfma_f32_16x16x32_bf16 v[32:35], v[152:155], v[184:187], v[32:35]
	v_mfma_f32_16x16x32_bf16 v[20:23], v[144:147], v[192:195], v[20:23]
	v_mfma_f32_16x16x32_bf16 v[16:19], v[152:155], v[192:195], v[16:19]
	v_mfma_f32_16x16x32_bf16 v[4:7], v[144:147], v[210:213], v[4:7]
	v_mfma_f32_16x16x32_bf16 v[0:3], v[152:155], v[210:213], v[0:3]
	v_mfma_f32_16x16x32_bf16 v[52:55], v[148:151], v[164:167], v[52:55]
	v_mfma_f32_16x16x32_bf16 v[48:51], v[156:159], v[164:167], v[48:51]
	v_mfma_f32_16x16x32_bf16 v[36:39], v[148:151], v[188:191], v[36:39]
	v_mfma_f32_16x16x32_bf16 v[32:35], v[156:159], v[188:191], v[32:35]
	v_mfma_f32_16x16x32_bf16 v[20:23], v[148:151], v[196:199], v[20:23]
	v_mfma_f32_16x16x32_bf16 v[16:19], v[156:159], v[196:199], v[16:19]
	v_mfma_f32_16x16x32_bf16 v[4:7], v[148:151], v[214:217], v[4:7]
	v_mfma_f32_16x16x32_bf16 v[0:3], v[156:159], v[214:217], v[0:3]
	s_barrier
	s_add_i32 s64, s64, 2
	s_add_u32 s62, s62, 0x100
	s_addc_u32 s63, s63, 0
	s_cmpk_gt_u32 s64, 0xa9
	s_mov_b64 s[46:47], s[48:49]
	s_cbranch_scc0 .LBB0_317
	s_and_b64 vcc, exec, s[42:43]
	s_cbranch_vccz .LBB0_320
	s_barrier

; #define PG8_STAGE(bufoff, gbase, voff) do { _Pragma("unroll") for (int _i = 0; _i < 2; ++_i) \
;         __builtin_amdgcn_global_load_lds((const unsigned*)((const char*)(gbase) + (voff)[_i]), (PG8_LAS unsigned*)(lds + (bufoff) + ldsw + _i * 8192), 16, 0, 0); } while (0)
; #define PG8_STAGE_NT(bufoff, gbase, voff) do { _Pragma("unroll") for (int _i = 0; _i < 2; ++_i) \
;         __builtin_amdgcn_global_load_lds((const unsigned*)((const char*)(gbase) + (voff)[_i]), (PG8_LAS unsigned*)(lds + (bufoff) + ldsw + _i * 8192), 16, 0, PG8_B_AUX); } while (0)
; #define PG8_LDA(dst, b, h) do { _Pragma("unroll") for (int m = 0; m < 4; ++m) _Pragma("unroll") for (int k = 0; k < 2; ++k) dst[m][k] = *(const PG8_LAS bf16x8*)(lds + PG8_SA(b, h) + aoff + m * 2048 + k * 1024); } while (0)
; #define PG8_LDB(dst, b, h) do { _Pragma("unroll") for (int n = 0; n < 2; ++n) _Pragma("unroll") for (int k = 0; k < 2; ++k) dst[n][k] = *(const PG8_LAS bf16x8*)(lds + PG8_SB(b, h) + boff + n * 2048 + k * 1024); } while (0)
; #define PG8_WAIT_V(n) asm volatile("s_waitcnt vmcnt(" #n ")" ::: "memory")
; #define PG8_WAIT_L(n) asm volatile("s_waitcnt lgkmcnt(" #n ")" ::: "memory")
; #define PG8_BAR __builtin_amdgcn_s_barrier()
; #define PG8_SCHED __builtin_amdgcn_sched_barrier(0)
; template <class Epi, class Sched, bool ALIGN_EPI = false, bool SP2 = false>
; __device__ __forceinline__ void gemm_phase(PG8_LAS unsigned char* lds, const Gemm g, const Sched& S, const Epi& E, int wid) {
;     ...
;             const bool last = (t == nt - 2);
;             const char* a1 = cA + (size_t)(t + 1) * kstep;
;             const char* a2 = last ? nA : cA + (size_t)(t + 2) * kstep; const char* b2 = last ? nB : cB + (size_t)(t + 2) * kstep;
;             const char* a3 = a2 + kstep; const char* b3 = b2 + kstep;
;             if (last && has_next) S.a_ready(nxt);
;             if constexpr (SP2) {
;             PG8_LDB(B0, 0, 0); PG8_LDB(B1, 0, 1); PG8_SCHED; PG8_LDA(At, 0, 0); PG8_STAGE(PG8_SA(1, 1), a1 + hstepA, voffA);
;             PG8_WAIT_V(8); PG8_WAIT_L(0); PG8_BAR; PG8_MMA(0, 0, At, B0); PG8_MMA(0, 1, At, B1); PG8_BAR; PG8_SCHED;
;             PG8_LDA(At, 0, 1); PG8_STAGE_NT(PG8_SB(0, 0), b2, voffB); PG8_STAGE_NT(PG8_SB(0, 1), b2 + hstepB, voffB); PG8_STAGE(PG8_SA(0, 0), a2, voffA);
;             PG8_WAIT_V(8); PG8_WAIT_L(0); PG8_BAR; PG8_MMA(1, 0, At, B0); PG8_MMA(1, 1, At, B1); PG8_BAR; PG8_SCHED;
.LBB0_426:
	ds_read_b128 v[144:147], v161
	ds_read_b128 v[148:151], v161 offset:1024
	ds_read_b128 v[152:155], v161 offset:2048
	ds_read_b128 v[166:169], v161 offset:3072
	ds_read_b128 v[170:173], v162
	ds_read_b128 v[174:177], v162 offset:1024
	ds_read_b128 v[178:181], v162 offset:2048
	ds_read_b128 v[182:185], v162 offset:3072
	s_add_u32 s4, s46, 0x100
	s_addc_u32 s5, s47, 0
	s_add_u32 s98, s46, 0x80
	s_addc_u32 s99, s47, 0
	s_add_u32 s100, s46, 0x104080
	s_addc_u32 s101, s47, 0
	s_cmp_eq_u32 s64, 60
	s_cselect_b32 s51, s43, s5
	s_cselect_b32 s50, s42, s4
	s_cselect_b32 s49, s45, s63
	s_cselect_b32 s48, s44, s62
	s_add_i32 m0, s23, 0xc000
	ds_read_b128 v[186:189], v163
	ds_read_b128 v[190:193], v163 offset:1024
	ds_read_b128 v[194:197], v163 offset:2048
	ds_read_b128 v[198:201], v163 offset:3072
	ds_read_b128 v[202:205], v163 offset:4096
	ds_read_b128 v[206:209], v163 offset:5120
	ds_read_b128 v[210:213], v163 offset:6144
	ds_read_b128 v[214:217], v163 offset:7168
	global_load_lds_dwordx4 v134, s[100:101]
	s_add_i32 m0, s23, 0xe000
	s_nop 0
	global_load_lds_dwordx4 v130, s[100:101]
	s_mov_b32 m0, s53
	s_nop 0
	global_load_lds_dwordx4 v134, s[98:99]
	s_mov_b32 m0, s54
	s_nop 0
	global_load_lds_dwordx4 v130, s[98:99]
	s_waitcnt vmcnt(8)
	s_waitcnt lgkmcnt(0)
	s_barrier
	v_mfma_f32_16x16x32_bf16 v[124:127], v[144:147], v[186:189], v[124:127]
	v_mfma_f32_16x16x32_bf16 v[120:123], v[152:155], v[186:189], v[120:123]
	v_mfma_f32_16x16x32_bf16 v[116:119], v[144:147], v[194:197], v[116:119]
	v_mfma_f32_16x16x32_bf16 v[112:115], v[152:155], v[194:197], v[112:115]
	v_mfma_f32_16x16x32_bf16 v[92:95], v[144:147], v[202:205], v[92:95]
	v_mfma_f32_16x16x32_bf16 v[88:91], v[152:155], v[202:205], v[88:91]
	v_mfma_f32_16x16x32_bf16 v[76:79], v[144:147], v[210:213], v[76:79]
	v_mfma_f32_16x16x32_bf16 v[72:75], v[152:155], v[210:213], v[72:75]
	v_mfma_f32_16x16x32_bf16 v[124:127], v[148:151], v[190:193], v[124:127]
	v_mfma_f32_16x16x32_bf16 v[120:123], v[166:169], v[190:193], v[120:123]
	v_mfma_f32_16x16x32_bf16 v[116:119], v[148:151], v[198:201], v[116:119]
	v_mfma_f32_16x16x32_bf16 v[112:115], v[166:169], v[198:201], v[112:115]
	v_mfma_f32_16x16x32_bf16 v[92:95], v[148:151], v[206:209], v[92:95]
	v_mfma_f32_16x16x32_bf16 v[88:91], v[166:169], v[206:209], v[88:91]
	v_mfma_f32_16x16x32_bf16 v[76:79], v[148:151], v[214:217], v[76:79]
	v_mfma_f32_16x16x32_bf16 v[72:75], v[166:169], v[214:217], v[72:75]
	v_mfma_f32_16x16x32_bf16 v[108:111], v[170:173], v[186:189], v[108:111]
	v_mfma_f32_16x16x32_bf16 v[104:107], v[178:181], v[186:189], v[104:107]
	v_mfma_f32_16x16x32_bf16 v[100:103], v[170:173], v[194:197], v[100:103]
	v_mfma_f32_16x16x32_bf16 v[96:99], v[178:181], v[194:197], v[96:99]
	v_mfma_f32_16x16x32_bf16 v[84:87], v[170:173], v[202:205], v[84:87]
	v_mfma_f32_16x16x32_bf16 v[80:83], v[178:181], v[202:205], v[80:83]
	v_mfma_f32_16x16x32_bf16 v[68:71], v[170:173], v[210:213], v[68:71]
	v_mfma_f32_16x16x32_bf16 v[64:67], v[178:181], v[210:213], v[64:67]
	v_mfma_f32_16x16x32_bf16 v[108:111], v[174:177], v[190:193], v[108:111]
	v_mfma_f32_16x16x32_bf16 v[104:107], v[182:185], v[190:193], v[104:107]
	v_mfma_f32_16x16x32_bf16 v[100:103], v[174:177], v[198:201], v[100:103]
	v_mfma_f32_16x16x32_bf16 v[96:99], v[182:185], v[198:201], v[96:99]
	v_mfma_f32_16x16x32_bf16 v[84:87], v[174:177], v[206:209], v[84:87]
	v_mfma_f32_16x16x32_bf16 v[80:83], v[182:185], v[206:209], v[80:83]
	v_mfma_f32_16x16x32_bf16 v[68:71], v[174:177], v[214:217], v[68:71]
	v_mfma_f32_16x16x32_bf16 v[64:67], v[182:185], v[214:217], v[64:67]
	s_barrier
	s_add_i32 s46, s56, s17
	s_mov_b32 m0, s46
	ds_read_b128 v[186:189], v163 offset:16384
	ds_read_b128 v[190:193], v163 offset:17408
	ds_read_b128 v[194:197], v163 offset:18432
	ds_read_b128 v[198:201], v163 offset:19456
	ds_read_b128 v[202:205], v163 offset:20480
	ds_read_b128 v[206:209], v163 offset:21504
	ds_read_b128 v[210:213], v163 offset:22528
	ds_read_b128 v[214:217], v163 offset:23552
	global_load_lds_dwordx4 v132, s[48:49]
	s_add_i32 m0, s46, 0x2000
	s_add_u32 s46, s48, 0x104000
	s_addc_u32 s47, s49, 0
	s_add_i32 s65, s57, s17
	global_load_lds_dwordx4 v128, s[48:49]
	s_mov_b32 m0, s65
	s_nop 0
	global_load_lds_dwordx4 v132, s[46:47]
	s_add_i32 m0, s65, 0x2000
	s_nop 0
	global_load_lds_dwordx4 v128, s[46:47]
	s_waitcnt vmcnt(4)
	s_waitcnt lgkmcnt(0)
	s_barrier
	v_mfma_f32_16x16x32_bf16 v[60:63], v[144:147], v[186:189], v[60:63]
	v_mfma_f32_16x16x32_bf16 v[56:59], v[152:155], v[186:189], v[56:59]
	v_mfma_f32_16x16x32_bf16 v[44:47], v[144:147], v[194:197], v[44:47]
	v_mfma_f32_16x16x32_bf16 v[40:43], v[152:155], v[194:197], v[40:43]
	v_mfma_f32_16x16x32_bf16 v[28:31], v[144:147], v[202:205], v[28:31]
	v_mfma_f32_16x16x32_bf16 v[24:27], v[152:155], v[202:205], v[24:27]
	v_mfma_f32_16x16x32_bf16 v[12:15], v[144:147], v[210:213], v[12:15]
	v_mfma_f32_16x16x32_bf16 v[8:11], v[152:155], v[210:213], v[8:11]
	v_mfma_f32_16x16x32_bf16 v[60:63], v[148:151], v[190:193], v[60:63]
	v_mfma_f32_16x16x32_bf16 v[56:59], v[166:169], v[190:193], v[56:59]
	v_mfma_f32_16x16x32_bf16 v[44:47], v[148:151], v[198:201], v[44:47]
	v_mfma_f32_16x16x32_bf16 v[40:43], v[166:169], v[198:201], v[40:43]
	v_mfma_f32_16x16x32_bf16 v[28:31], v[148:151], v[206:209], v[28:31]
	v_mfma_f32_16x16x32_bf16 v[24:27], v[166:169], v[206:209], v[24:27]
	v_mfma_f32_16x16x32_bf16 v[12:15], v[148:151], v[214:217], v[12:15]
	v_mfma_f32_16x16x32_bf16 v[8:11], v[166:169], v[214:217], v[8:11]
	v_mfma_f32_16x16x32_bf16 v[52:55], v[170:173], v[186:189], v[52:55]
	v_mfma_f32_16x16x32_bf16 v[48:51], v[178:181], v[186:189], v[48:51]
	v_mfma_f32_16x16x32_bf16 v[36:39], v[170:173], v[194:197], v[36:39]
	v_mfma_f32_16x16x32_bf16 v[32:35], v[178:181], v[194:197], v[32:35]
	v_mfma_f32_16x16x32_bf16 v[20:23], v[170:173], v[202:205], v[20:23]
	v_mfma_f32_16x16x32_bf16 v[16:19], v[178:181], v[202:205], v[16:19]
	v_mfma_f32_16x16x32_bf16 v[4:7], v[170:173], v[210:213], v[4:7]
	v_mfma_f32_16x16x32_bf16 v[0:3], v[178:181], v[210:213], v[0:3]
	v_mfma_f32_16x16x32_bf16 v[52:55], v[174:177], v[190:193], v[52:55]
	v_mfma_f32_16x16x32_bf16 v[48:51], v[182:185], v[190:193], v[48:51]
	v_mfma_f32_16x16x32_bf16 v[36:39], v[174:177], v[198:201], v[36:39]
	v_mfma_f32_16x16x32_bf16 v[32:35], v[182:185], v[198:201], v[32:35]
	v_mfma_f32_16x16x32_bf16 v[20:23], v[174:177], v[206:209], v[20:23]
	v_mfma_f32_16x16x32_bf16 v[16:19], v[182:185], v[206:209], v[16:19]
	v_mfma_f32_16x16x32_bf16 v[4:7], v[174:177], v[214:217], v[4:7]
	v_mfma_f32_16x16x32_bf16 v[0:3], v[182:185], v[214:217], v[0:3]
	s_barrier
; #define PG8_STAGE(bufoff, gbase, voff) do { _Pragma("unroll") for (int _i = 0; _i < 2; ++_i) \
;         __builtin_amdgcn_global_load_lds((const unsigned*)((const char*)(gbase) + (voff)[_i]), (PG8_LAS unsigned*)(lds + (bufoff) + ldsw + _i * 8192), 16, 0, 0); } while (0)
; #define PG8_STAGE_NT(bufoff, gbase, voff) do { _Pragma("unroll") for (int _i = 0; _i < 2; ++_i) \
;         __builtin_amdgcn_global_load_lds((const unsigned*)((const char*)(gbase) + (voff)[_i]), (PG8_LAS unsigned*)(lds + (bufoff) + ldsw + _i * 8192), 16, 0, PG8_B_AUX); } while (0)
; #define PG8_LDA(dst, b, h) do { _Pragma("unroll") for (int m = 0; m < 4; ++m) _Pragma("unroll") for (int k = 0; k < 2; ++k) dst[m][k] = *(const PG8_LAS bf16x8*)(lds + PG8_SA(b, h) + aoff + m * 2048 + k * 1024); } while (0)
; #define PG8_LDB(dst, b, h) do { _Pragma("unroll") for (int n = 0; n < 2; ++n) _Pragma("unroll") for (int k = 0; k < 2; ++k) dst[n][k] = *(const PG8_LAS bf16x8*)(lds + PG8_SB(b, h) + boff + n * 2048 + k * 1024); } while (0)
; #define PG8_MMA(ai, bj, At, Bt) do { __builtin_amdgcn_s_setprio(1); _Pragma("unroll") for (int m = 0; m < 4; ++m) _Pragma("unroll") for (int n = 0; n < 2; ++n) _Pragma("unroll") for (int k = 0; k < 2; ++k) \
;         acc[ai][bj][m][n] = __builtin_amdgcn_mfma_f32_16x16x32_bf16(Bt[n][k], At[m][k], acc[ai][bj][m][n], 0, 0, 0); __builtin_amdgcn_s_setprio(0); } while (0)
; #define PG8_WAIT_V(n) asm volatile("s_waitcnt vmcnt(" #n ")" ::: "memory")
; #define PG8_WAIT_L(n) asm volatile("s_waitcnt lgkmcnt(" #n ")" ::: "memory")
; #define PG8_BAR __builtin_amdgcn_s_barrier()
; #define PG8_SCHED __builtin_amdgcn_sched_barrier(0)
; template <class Epi, class Sched, bool ALIGN_EPI = false, bool SP2 = false>
; __device__ __forceinline__ void gemm_phase(PG8_LAS unsigned char* lds, const Gemm g, const Sched& S, const Epi& E, int wid) {
;     ...
;             PG8_LDB(B0, 1, 0); PG8_LDB(B1, 1, 1); PG8_SCHED; PG8_LDA(At, 1, 0); PG8_STAGE(PG8_SA(0, 1), a2 + hstepA, voffA);
;             PG8_WAIT_V(8); PG8_WAIT_L(0); PG8_BAR; PG8_MMA(0, 0, At, B0); PG8_MMA(0, 1, At, B1); PG8_BAR; PG8_SCHED;
;             PG8_LDA(At, 1, 1); PG8_STAGE_NT(PG8_SB(1, 0), b3, voffB); PG8_STAGE_NT(PG8_SB(1, 1), b3 + hstepB, voffB); PG8_STAGE(PG8_SA(1, 0), a3, voffA);
;             PG8_WAIT_V(8); PG8_WAIT_L(0); PG8_BAR; PG8_MMA(1, 0, At, B0); PG8_MMA(1, 1, At, B1); PG8_BAR; PG8_SCHED;
	s_add_i32 s65, 0, 0x18000
	v_add_u32_e32 v165, s65, v159
	s_add_i32 s66, 0, 0x1c000
	ds_read_b128 v[144:147], v165
	ds_read_b128 v[148:151], v165 offset:1024
	ds_read_b128 v[152:155], v165 offset:2048
	ds_read_b128 v[166:169], v165 offset:3072
	v_add_u32_e32 v165, s66, v159
	ds_read_b128 v[170:173], v165
	ds_read_b128 v[174:177], v165 offset:1024
	ds_read_b128 v[178:181], v165 offset:2048
	ds_read_b128 v[182:185], v165 offset:3072
	s_add_u32 s46, s50, 0x104000
	s_addc_u32 s47, s51, 0
	s_mov_b32 m0, s25
	ds_read_b128 v[186:189], v163 offset:32768
	ds_read_b128 v[190:193], v163 offset:33792
	ds_read_b128 v[194:197], v163 offset:34816
	ds_read_b128 v[198:201], v163 offset:35840
	ds_read_b128 v[202:205], v163 offset:36864
	ds_read_b128 v[206:209], v163 offset:37888
	ds_read_b128 v[210:213], v163 offset:38912
	ds_read_b128 v[214:217], v163 offset:39936
	global_load_lds_dwordx4 v134, s[46:47]
	s_mov_b32 m0, s29
	s_nop 0
	global_load_lds_dwordx4 v130, s[46:47]
	s_mov_b32 m0, s23
	s_nop 0
	global_load_lds_dwordx4 v134, s[50:51]
	s_mov_b32 m0, s24
	s_nop 0
	global_load_lds_dwordx4 v130, s[50:51]
	s_waitcnt vmcnt(8)
	s_waitcnt lgkmcnt(0)
	s_barrier
	v_mfma_f32_16x16x32_bf16 v[124:127], v[144:147], v[186:189], v[124:127]
	v_mfma_f32_16x16x32_bf16 v[120:123], v[152:155], v[186:189], v[120:123]
	v_mfma_f32_16x16x32_bf16 v[116:119], v[144:147], v[194:197], v[116:119]
	v_mfma_f32_16x16x32_bf16 v[112:115], v[152:155], v[194:197], v[112:115]
	v_mfma_f32_16x16x32_bf16 v[92:95], v[144:147], v[202:205], v[92:95]
	v_mfma_f32_16x16x32_bf16 v[88:91], v[152:155], v[202:205], v[88:91]
	v_mfma_f32_16x16x32_bf16 v[76:79], v[144:147], v[210:213], v[76:79]
	v_mfma_f32_16x16x32_bf16 v[72:75], v[152:155], v[210:213], v[72:75]
	v_mfma_f32_16x16x32_bf16 v[124:127], v[148:151], v[190:193], v[124:127]
	v_mfma_f32_16x16x32_bf16 v[120:123], v[166:169], v[190:193], v[120:123]
	v_mfma_f32_16x16x32_bf16 v[116:119], v[148:151], v[198:201], v[116:119]
	v_mfma_f32_16x16x32_bf16 v[112:115], v[166:169], v[198:201], v[112:115]
	v_mfma_f32_16x16x32_bf16 v[92:95], v[148:151], v[206:209], v[92:95]
	v_mfma_f32_16x16x32_bf16 v[88:91], v[166:169], v[206:209], v[88:91]
	v_mfma_f32_16x16x32_bf16 v[76:79], v[148:151], v[214:217], v[76:79]
	v_mfma_f32_16x16x32_bf16 v[72:75], v[166:169], v[214:217], v[72:75]
	v_mfma_f32_16x16x32_bf16 v[108:111], v[170:173], v[186:189], v[108:111]
	v_mfma_f32_16x16x32_bf16 v[104:107], v[178:181], v[186:189], v[104:107]
	v_mfma_f32_16x16x32_bf16 v[100:103], v[170:173], v[194:197], v[100:103]
	v_mfma_f32_16x16x32_bf16 v[96:99], v[178:181], v[194:197], v[96:99]
	v_mfma_f32_16x16x32_bf16 v[84:87], v[170:173], v[202:205], v[84:87]
	v_mfma_f32_16x16x32_bf16 v[80:83], v[178:181], v[202:205], v[80:83]
	v_mfma_f32_16x16x32_bf16 v[68:71], v[170:173], v[210:213], v[68:71]
	v_mfma_f32_16x16x32_bf16 v[64:67], v[178:181], v[210:213], v[64:67]
	v_mfma_f32_16x16x32_bf16 v[108:111], v[174:177], v[190:193], v[108:111]
	v_mfma_f32_16x16x32_bf16 v[104:107], v[182:185], v[190:193], v[104:107]
	v_mfma_f32_16x16x32_bf16 v[100:103], v[174:177], v[198:201], v[100:103]
	v_mfma_f32_16x16x32_bf16 v[96:99], v[182:185], v[198:201], v[96:99]
	v_mfma_f32_16x16x32_bf16 v[84:87], v[174:177], v[206:209], v[84:87]
	v_mfma_f32_16x16x32_bf16 v[80:83], v[182:185], v[206:209], v[80:83]
	v_mfma_f32_16x16x32_bf16 v[68:71], v[174:177], v[214:217], v[68:71]
	v_mfma_f32_16x16x32_bf16 v[64:67], v[182:185], v[214:217], v[64:67]
	s_barrier
	s_add_i32 s46, s65, s17
	s_mov_b32 m0, s46
	s_add_u32 s98, s48, 0x80
	s_addc_u32 s99, s49, 0
	ds_read_b128 v[186:189], v163 offset:49152
	ds_read_b128 v[190:193], v163 offset:50176
	ds_read_b128 v[194:197], v163 offset:51200
	ds_read_b128 v[198:201], v163 offset:52224
	ds_read_b128 v[202:205], v163 offset:53248
	ds_read_b128 v[206:209], v163 offset:54272
	ds_read_b128 v[210:213], v163 offset:55296
	ds_read_b128 v[214:217], v163 offset:56320
	global_load_lds_dwordx4 v132, s[98:99]
	s_add_i32 m0, s46, 0x2000
	s_add_u32 s46, s48, 0x104080
	s_addc_u32 s47, s49, 0
	s_add_i32 s48, s66, s17
	global_load_lds_dwordx4 v128, s[98:99]
	s_mov_b32 m0, s48
	s_nop 0
	global_load_lds_dwordx4 v132, s[46:47]
	s_add_i32 m0, s48, 0x2000
	s_nop 0
	global_load_lds_dwordx4 v128, s[46:47]
	s_waitcnt vmcnt(4)
	s_waitcnt lgkmcnt(0)
	s_barrier
	v_mfma_f32_16x16x32_bf16 v[60:63], v[144:147], v[186:189], v[60:63]
	v_mfma_f32_16x16x32_bf16 v[56:59], v[152:155], v[186:189], v[56:59]
	v_mfma_f32_16x16x32_bf16 v[44:47], v[144:147], v[194:197], v[44:47]
	v_mfma_f32_16x16x32_bf16 v[40:43], v[152:155], v[194:197], v[40:43]
	v_mfma_f32_16x16x32_bf16 v[28:31], v[144:147], v[202:205], v[28:31]
	v_mfma_f32_16x16x32_bf16 v[24:27], v[152:155], v[202:205], v[24:27]
	v_mfma_f32_16x16x32_bf16 v[12:15], v[144:147], v[210:213], v[12:15]
	v_mfma_f32_16x16x32_bf16 v[8:11], v[152:155], v[210:213], v[8:11]
	v_mfma_f32_16x16x32_bf16 v[60:63], v[148:151], v[190:193], v[60:63]
	v_mfma_f32_16x16x32_bf16 v[56:59], v[166:169], v[190:193], v[56:59]
	v_mfma_f32_16x16x32_bf16 v[44:47], v[148:151], v[198:201], v[44:47]
	v_mfma_f32_16x16x32_bf16 v[40:43], v[166:169], v[198:201], v[40:43]
	v_mfma_f32_16x16x32_bf16 v[28:31], v[148:151], v[206:209], v[28:31]
	v_mfma_f32_16x16x32_bf16 v[24:27], v[166:169], v[206:209], v[24:27]
	v_mfma_f32_16x16x32_bf16 v[12:15], v[148:151], v[214:217], v[12:15]
	v_mfma_f32_16x16x32_bf16 v[8:11], v[166:169], v[214:217], v[8:11]
	v_mfma_f32_16x16x32_bf16 v[52:55], v[170:173], v[186:189], v[52:55]
	v_mfma_f32_16x16x32_bf16 v[48:51], v[178:181], v[186:189], v[48:51]
	v_mfma_f32_16x16x32_bf16 v[36:39], v[170:173], v[194:197], v[36:39]
	v_mfma_f32_16x16x32_bf16 v[32:35], v[178:181], v[194:197], v[32:35]
	v_mfma_f32_16x16x32_bf16 v[20:23], v[170:173], v[202:205], v[20:23]
	v_mfma_f32_16x16x32_bf16 v[16:19], v[178:181], v[202:205], v[16:19]
	v_mfma_f32_16x16x32_bf16 v[4:7], v[170:173], v[210:213], v[4:7]
	v_mfma_f32_16x16x32_bf16 v[0:3], v[178:181], v[210:213], v[0:3]
	v_mfma_f32_16x16x32_bf16 v[52:55], v[174:177], v[190:193], v[52:55]
	v_mfma_f32_16x16x32_bf16 v[48:51], v[182:185], v[190:193], v[48:51]
	v_mfma_f32_16x16x32_bf16 v[36:39], v[174:177], v[198:201], v[36:39]
	v_mfma_f32_16x16x32_bf16 v[32:35], v[182:185], v[198:201], v[32:35]
	v_mfma_f32_16x16x32_bf16 v[20:23], v[174:177], v[206:209], v[20:23]
	v_mfma_f32_16x16x32_bf16 v[16:19], v[182:185], v[206:209], v[16:19]
	v_mfma_f32_16x16x32_bf16 v[4:7], v[174:177], v[214:217], v[4:7]
	v_mfma_f32_16x16x32_bf16 v[0:3], v[182:185], v[214:217], v[0:3]
	s_barrier
	s_add_i32 s64, s64, 2
	s_add_u32 s62, s62, 0x100
	s_addc_u32 s63, s63, 0
	s_cmp_gt_u32 s64, 61
	s_mov_b64 s[46:47], s[4:5]
	s_cbranch_scc0 .LBB0_426
	s_and_b64 vcc, exec, s[40:41]
	s_cbranch_vccz .LBB0_429
	s_barrier

; #define PG8_STAGE(bufoff, gbase, voff) do { _Pragma("unroll") for (int _i = 0; _i < 2; ++_i) \
;         __builtin_amdgcn_global_load_lds((const unsigned*)((const char*)(gbase) + (voff)[_i]), (PG8_LAS unsigned*)(lds + (bufoff) + ldsw + _i * 8192), 16, 0, 0); } while (0)
; #define PG8_STAGE_NT(bufoff, gbase, voff) do { _Pragma("unroll") for (int _i = 0; _i < 2; ++_i) \
;         __builtin_amdgcn_global_load_lds((const unsigned*)((const char*)(gbase) + (voff)[_i]), (PG8_LAS unsigned*)(lds + (bufoff) + ldsw + _i * 8192), 16, 0, PG8_B_AUX); } while (0)
; #define PG8_LDA(dst, b, h) do { _Pragma("unroll") for (int m = 0; m < 4; ++m) _Pragma("unroll") for (int k = 0; k < 2; ++k) dst[m][k] = *(const PG8_LAS bf16x8*)(lds + PG8_SA(b, h) + aoff + m * 2048 + k * 1024); } while (0)
; #define PG8_LDB(dst, b, h) do { _Pragma("unroll") for (int n = 0; n < 2; ++n) _Pragma("unroll") for (int k = 0; k < 2; ++k) dst[n][k] = *(const PG8_LAS bf16x8*)(lds + PG8_SB(b, h) + boff + n * 2048 + k * 1024); } while (0)
; #define PG8_WAIT_V(n) asm volatile("s_waitcnt vmcnt(" #n ")" ::: "memory")
; #define PG8_WAIT_L(n) asm volatile("s_waitcnt lgkmcnt(" #n ")" ::: "memory")
; #define PG8_BAR __builtin_amdgcn_s_barrier()
; #define PG8_SCHED __builtin_amdgcn_sched_barrier(0)
; template <class Epi, class Sched, bool ALIGN_EPI = false, bool SP2 = false>
; __device__ __forceinline__ void gemm_phase(PG8_LAS unsigned char* lds, const Gemm g, const Sched& S, const Epi& E, int wid) {
;     ...
;             const bool last = (t == nt - 2);
;             const char* a1 = cA + (size_t)(t + 1) * kstep;
;             const char* a2 = last ? nA : cA + (size_t)(t + 2) * kstep; const char* b2 = last ? nB : cB + (size_t)(t + 2) * kstep;
;             const char* a3 = a2 + kstep; const char* b3 = b2 + kstep;
;             if (last && has_next) S.a_ready(nxt);
;             if constexpr (SP2) {
;             PG8_LDB(B0, 0, 0); PG8_LDB(B1, 0, 1); PG8_SCHED; PG8_LDA(At, 0, 0); PG8_STAGE(PG8_SA(1, 1), a1 + hstepA, voffA);
;             PG8_WAIT_V(8); PG8_WAIT_L(0); PG8_BAR; PG8_MMA(0, 0, At, B0); PG8_MMA(0, 1, At, B1); PG8_BAR; PG8_SCHED;
;             PG8_LDA(At, 0, 1); PG8_STAGE_NT(PG8_SB(0, 0), b2, voffB); PG8_STAGE_NT(PG8_SB(0, 1), b2 + hstepB, voffB); PG8_STAGE(PG8_SA(0, 0), a2, voffA);
;             PG8_WAIT_V(8); PG8_WAIT_L(0); PG8_BAR; PG8_MMA(1, 0, At, B0); PG8_MMA(1, 1, At, B1); PG8_BAR; PG8_SCHED;
.LBB0_1037:
	ds_read_b128 v[104:107], v221
	ds_read_b128 v[116:119], v221 offset:1024
	ds_read_b128 v[128:131], v221 offset:2048
	ds_read_b128 v[140:143], v221 offset:3072
	ds_read_b128 v[144:147], v222
	ds_read_b128 v[148:151], v222 offset:1024
	ds_read_b128 v[152:155], v222 offset:2048
	ds_read_b128 v[156:159], v222 offset:3072
	s_add_u32 s52, s50, 0x100
	s_addc_u32 s53, s51, 0
	s_add_u32 s98, s50, 0x80
	s_addc_u32 s99, s51, 0
	s_add_u32 s100, s50, 0x104080
	s_addc_u32 s101, s51, 0
	s_cmp_eq_u32 s67, 60
	s_cselect_b32 s57, s7, s53
	s_cselect_b32 s56, s6, s52
	s_cselect_b32 s55, s49, s66
	s_cselect_b32 s54, s48, s65
	s_add_i32 m0, s17, 0xc000
	ds_read_b128 v[160:163], v223
	ds_read_b128 v[164:167], v223 offset:1024
	ds_read_b128 v[168:171], v223 offset:2048
	ds_read_b128 v[172:175], v223 offset:3072
	ds_read_b128 v[176:179], v223 offset:4096
	ds_read_b128 v[180:183], v223 offset:5120
	ds_read_b128 v[200:203], v223 offset:6144
	ds_read_b128 v[204:207], v223 offset:7168
	global_load_lds_dwordx4 v184, s[100:101]
	s_add_i32 m0, s17, 0xe000
	s_nop 0
	global_load_lds_dwordx4 v188, s[100:101]
	s_mov_b32 m0, s25
	s_nop 0
	global_load_lds_dwordx4 v184, s[98:99]
	s_mov_b32 m0, s29
	s_nop 0
	global_load_lds_dwordx4 v188, s[98:99]
	s_waitcnt vmcnt(8)
	s_waitcnt lgkmcnt(0)
	s_barrier
	v_mfma_f32_16x16x32_bf16 v[136:139], v[104:107], v[160:163], v[136:139]
	v_mfma_f32_16x16x32_bf16 v[132:135], v[128:131], v[160:163], v[132:135]
	v_mfma_f32_16x16x32_bf16 v[112:115], v[104:107], v[168:171], v[112:115]
	v_mfma_f32_16x16x32_bf16 v[108:111], v[128:131], v[168:171], v[108:111]
	v_mfma_f32_16x16x32_bf16 v[92:95], v[104:107], v[176:179], v[92:95]
	v_mfma_f32_16x16x32_bf16 v[88:91], v[128:131], v[176:179], v[88:91]
	v_mfma_f32_16x16x32_bf16 v[76:79], v[104:107], v[200:203], v[76:79]
	v_mfma_f32_16x16x32_bf16 v[72:75], v[128:131], v[200:203], v[72:75]
	v_mfma_f32_16x16x32_bf16 v[136:139], v[116:119], v[164:167], v[136:139]
	v_mfma_f32_16x16x32_bf16 v[132:135], v[140:143], v[164:167], v[132:135]
	v_mfma_f32_16x16x32_bf16 v[112:115], v[116:119], v[172:175], v[112:115]
	v_mfma_f32_16x16x32_bf16 v[108:111], v[140:143], v[172:175], v[108:111]
	v_mfma_f32_16x16x32_bf16 v[92:95], v[116:119], v[180:183], v[92:95]
	v_mfma_f32_16x16x32_bf16 v[88:91], v[140:143], v[180:183], v[88:91]
	v_mfma_f32_16x16x32_bf16 v[76:79], v[116:119], v[204:207], v[76:79]
	v_mfma_f32_16x16x32_bf16 v[72:75], v[140:143], v[204:207], v[72:75]
	v_mfma_f32_16x16x32_bf16 v[124:127], v[144:147], v[160:163], v[124:127]
	v_mfma_f32_16x16x32_bf16 v[120:123], v[152:155], v[160:163], v[120:123]
	v_mfma_f32_16x16x32_bf16 v[100:103], v[144:147], v[168:171], v[100:103]
	v_mfma_f32_16x16x32_bf16 v[96:99], v[152:155], v[168:171], v[96:99]
	v_mfma_f32_16x16x32_bf16 v[84:87], v[144:147], v[176:179], v[84:87]
	v_mfma_f32_16x16x32_bf16 v[80:83], v[152:155], v[176:179], v[80:83]
	v_mfma_f32_16x16x32_bf16 v[68:71], v[144:147], v[200:203], v[68:71]
	v_mfma_f32_16x16x32_bf16 v[64:67], v[152:155], v[200:203], v[64:67]
	v_mfma_f32_16x16x32_bf16 v[124:127], v[148:151], v[164:167], v[124:127]
	v_mfma_f32_16x16x32_bf16 v[120:123], v[156:159], v[164:167], v[120:123]
	v_mfma_f32_16x16x32_bf16 v[100:103], v[148:151], v[172:175], v[100:103]
	v_mfma_f32_16x16x32_bf16 v[96:99], v[156:159], v[172:175], v[96:99]
	v_mfma_f32_16x16x32_bf16 v[84:87], v[148:151], v[180:183], v[84:87]
	v_mfma_f32_16x16x32_bf16 v[80:83], v[156:159], v[180:183], v[80:83]
	v_mfma_f32_16x16x32_bf16 v[68:71], v[148:151], v[204:207], v[68:71]
	v_mfma_f32_16x16x32_bf16 v[64:67], v[156:159], v[204:207], v[64:67]
	s_barrier
	s_add_i32 s50, s60, s9
	s_mov_b32 m0, s50
	ds_read_b128 v[160:163], v223 offset:16384
	ds_read_b128 v[164:167], v223 offset:17408
	ds_read_b128 v[168:171], v223 offset:18432
	ds_read_b128 v[172:175], v223 offset:19456
	ds_read_b128 v[176:179], v223 offset:20480
	ds_read_b128 v[180:183], v223 offset:21504
	ds_read_b128 v[200:203], v223 offset:22528
	ds_read_b128 v[204:207], v223 offset:23552
	global_load_lds_dwordx4 v186, s[54:55]
	s_add_i32 m0, s50, 0x2000
	s_add_u32 s50, s54, 0x104000
	s_addc_u32 s51, s55, 0
	s_add_i32 s68, s61, s9
	global_load_lds_dwordx4 v190, s[54:55]
	s_mov_b32 m0, s68
	s_nop 0
	global_load_lds_dwordx4 v186, s[50:51]
	s_add_i32 m0, s68, 0x2000
	s_nop 0
	global_load_lds_dwordx4 v190, s[50:51]
	s_waitcnt vmcnt(4)
	s_waitcnt lgkmcnt(0)
	s_barrier
	v_mfma_f32_16x16x32_bf16 v[60:63], v[104:107], v[160:163], v[60:63]
	v_mfma_f32_16x16x32_bf16 v[56:59], v[128:131], v[160:163], v[56:59]
	v_mfma_f32_16x16x32_bf16 v[44:47], v[104:107], v[168:171], v[44:47]
	v_mfma_f32_16x16x32_bf16 v[40:43], v[128:131], v[168:171], v[40:43]
	v_mfma_f32_16x16x32_bf16 v[28:31], v[104:107], v[176:179], v[28:31]
	v_mfma_f32_16x16x32_bf16 v[24:27], v[128:131], v[176:179], v[24:27]
	v_mfma_f32_16x16x32_bf16 v[12:15], v[104:107], v[200:203], v[12:15]
	v_mfma_f32_16x16x32_bf16 v[8:11], v[128:131], v[200:203], v[8:11]
	v_mfma_f32_16x16x32_bf16 v[60:63], v[116:119], v[164:167], v[60:63]
	v_mfma_f32_16x16x32_bf16 v[56:59], v[140:143], v[164:167], v[56:59]
	v_mfma_f32_16x16x32_bf16 v[44:47], v[116:119], v[172:175], v[44:47]
	v_mfma_f32_16x16x32_bf16 v[40:43], v[140:143], v[172:175], v[40:43]
	v_mfma_f32_16x16x32_bf16 v[28:31], v[116:119], v[180:183], v[28:31]
	v_mfma_f32_16x16x32_bf16 v[24:27], v[140:143], v[180:183], v[24:27]
	v_mfma_f32_16x16x32_bf16 v[12:15], v[116:119], v[204:207], v[12:15]
	v_mfma_f32_16x16x32_bf16 v[8:11], v[140:143], v[204:207], v[8:11]
	v_mfma_f32_16x16x32_bf16 v[52:55], v[144:147], v[160:163], v[52:55]
	v_mfma_f32_16x16x32_bf16 v[48:51], v[152:155], v[160:163], v[48:51]
	v_mfma_f32_16x16x32_bf16 v[36:39], v[144:147], v[168:171], v[36:39]
	v_mfma_f32_16x16x32_bf16 v[32:35], v[152:155], v[168:171], v[32:35]
	v_mfma_f32_16x16x32_bf16 v[20:23], v[144:147], v[176:179], v[20:23]
	v_mfma_f32_16x16x32_bf16 v[16:19], v[152:155], v[176:179], v[16:19]
	v_mfma_f32_16x16x32_bf16 v[4:7], v[144:147], v[200:203], v[4:7]
	v_mfma_f32_16x16x32_bf16 v[0:3], v[152:155], v[200:203], v[0:3]
	v_mfma_f32_16x16x32_bf16 v[52:55], v[148:151], v[164:167], v[52:55]
	v_mfma_f32_16x16x32_bf16 v[48:51], v[156:159], v[164:167], v[48:51]
	v_mfma_f32_16x16x32_bf16 v[36:39], v[148:151], v[172:175], v[36:39]
	v_mfma_f32_16x16x32_bf16 v[32:35], v[156:159], v[172:175], v[32:35]
	v_mfma_f32_16x16x32_bf16 v[20:23], v[148:151], v[180:183], v[20:23]
	v_mfma_f32_16x16x32_bf16 v[16:19], v[156:159], v[180:183], v[16:19]
	v_mfma_f32_16x16x32_bf16 v[4:7], v[148:151], v[204:207], v[4:7]
	v_mfma_f32_16x16x32_bf16 v[0:3], v[156:159], v[204:207], v[0:3]
	s_barrier
; #define PG8_STAGE(bufoff, gbase, voff) do { _Pragma("unroll") for (int _i = 0; _i < 2; ++_i) \
;         __builtin_amdgcn_global_load_lds((const unsigned*)((const char*)(gbase) + (voff)[_i]), (PG8_LAS unsigned*)(lds + (bufoff) + ldsw + _i * 8192), 16, 0, 0); } while (0)
; #define PG8_STAGE_NT(bufoff, gbase, voff) do { _Pragma("unroll") for (int _i = 0; _i < 2; ++_i) \
;         __builtin_amdgcn_global_load_lds((const unsigned*)((const char*)(gbase) + (voff)[_i]), (PG8_LAS unsigned*)(lds + (bufoff) + ldsw + _i * 8192), 16, 0, PG8_B_AUX); } while (0)
; #define PG8_LDA(dst, b, h) do { _Pragma("unroll") for (int m = 0; m < 4; ++m) _Pragma("unroll") for (int k = 0; k < 2; ++k) dst[m][k] = *(const PG8_LAS bf16x8*)(lds + PG8_SA(b, h) + aoff + m * 2048 + k * 1024); } while (0)
; #define PG8_LDB(dst, b, h) do { _Pragma("unroll") for (int n = 0; n < 2; ++n) _Pragma("unroll") for (int k = 0; k < 2; ++k) dst[n][k] = *(const PG8_LAS bf16x8*)(lds + PG8_SB(b, h) + boff + n * 2048 + k * 1024); } while (0)
; #define PG8_MMA(ai, bj, At, Bt) do { __builtin_amdgcn_s_setprio(1); _Pragma("unroll") for (int m = 0; m < 4; ++m) _Pragma("unroll") for (int n = 0; n < 2; ++n) _Pragma("unroll") for (int k = 0; k < 2; ++k) \
;         acc[ai][bj][m][n] = __builtin_amdgcn_mfma_f32_16x16x32_bf16(Bt[n][k], At[m][k], acc[ai][bj][m][n], 0, 0, 0); __builtin_amdgcn_s_setprio(0); } while (0)
; #define PG8_WAIT_V(n) asm volatile("s_waitcnt vmcnt(" #n ")" ::: "memory")
; #define PG8_WAIT_L(n) asm volatile("s_waitcnt lgkmcnt(" #n ")" ::: "memory")
; #define PG8_BAR __builtin_amdgcn_s_barrier()
; #define PG8_SCHED __builtin_amdgcn_sched_barrier(0)
; template <class Epi, class Sched, bool ALIGN_EPI = false, bool SP2 = false>
; __device__ __forceinline__ void gemm_phase(PG8_LAS unsigned char* lds, const Gemm g, const Sched& S, const Epi& E, int wid) {
;     ...
;             PG8_LDB(B0, 1, 0); PG8_LDB(B1, 1, 1); PG8_SCHED; PG8_LDA(At, 1, 0); PG8_STAGE(PG8_SA(0, 1), a2 + hstepA, voffA);
;             PG8_WAIT_V(8); PG8_WAIT_L(0); PG8_BAR; PG8_MMA(0, 0, At, B0); PG8_MMA(0, 1, At, B1); PG8_BAR; PG8_SCHED;
;             PG8_LDA(At, 1, 1); PG8_STAGE_NT(PG8_SB(1, 0), b3, voffB); PG8_STAGE_NT(PG8_SB(1, 1), b3 + hstepB, voffB); PG8_STAGE(PG8_SA(1, 0), a3, voffA);
;             PG8_WAIT_V(8); PG8_WAIT_L(0); PG8_BAR; PG8_MMA(1, 0, At, B0); PG8_MMA(1, 1, At, B1); PG8_BAR; PG8_SCHED;
	s_add_i32 s68, 0, 0x18000
	v_add_u32_e32 v140, s68, v219
	s_add_i32 s69, 0, 0x1c000
	ds_read_b128 v[104:107], v140
	ds_read_b128 v[116:119], v140 offset:1024
	ds_read_b128 v[128:131], v140 offset:2048
	ds_read_b128 v[140:143], v140 offset:3072
	v_add_u32_e32 v156, s69, v219
	ds_read_b128 v[144:147], v156
	ds_read_b128 v[148:151], v156 offset:1024
	ds_read_b128 v[152:155], v156 offset:2048
	ds_read_b128 v[156:159], v156 offset:3072
	s_add_u32 s50, s56, 0x104000
	s_addc_u32 s51, s57, 0
	s_mov_b32 m0, s22
	ds_read_b128 v[160:163], v223 offset:32768
	ds_read_b128 v[164:167], v223 offset:33792
	ds_read_b128 v[168:171], v223 offset:34816
	ds_read_b128 v[172:175], v223 offset:35840
	ds_read_b128 v[176:179], v223 offset:36864
	ds_read_b128 v[180:183], v223 offset:37888
	ds_read_b128 v[200:203], v223 offset:38912
	ds_read_b128 v[204:207], v223 offset:39936
	global_load_lds_dwordx4 v184, s[50:51]
	s_mov_b32 m0, s23
	s_nop 0
	global_load_lds_dwordx4 v188, s[50:51]
	s_mov_b32 m0, s17
	s_nop 0
	global_load_lds_dwordx4 v184, s[56:57]
	s_mov_b32 m0, s19
	s_nop 0
	global_load_lds_dwordx4 v188, s[56:57]
	s_waitcnt vmcnt(8)
	s_waitcnt lgkmcnt(0)
	s_barrier
	v_mfma_f32_16x16x32_bf16 v[136:139], v[104:107], v[160:163], v[136:139]
	v_mfma_f32_16x16x32_bf16 v[132:135], v[128:131], v[160:163], v[132:135]
	v_mfma_f32_16x16x32_bf16 v[112:115], v[104:107], v[168:171], v[112:115]
	v_mfma_f32_16x16x32_bf16 v[108:111], v[128:131], v[168:171], v[108:111]
	v_mfma_f32_16x16x32_bf16 v[92:95], v[104:107], v[176:179], v[92:95]
	v_mfma_f32_16x16x32_bf16 v[88:91], v[128:131], v[176:179], v[88:91]
	v_mfma_f32_16x16x32_bf16 v[76:79], v[104:107], v[200:203], v[76:79]
	v_mfma_f32_16x16x32_bf16 v[72:75], v[128:131], v[200:203], v[72:75]
	v_mfma_f32_16x16x32_bf16 v[136:139], v[116:119], v[164:167], v[136:139]
	v_mfma_f32_16x16x32_bf16 v[132:135], v[140:143], v[164:167], v[132:135]
	v_mfma_f32_16x16x32_bf16 v[112:115], v[116:119], v[172:175], v[112:115]
	v_mfma_f32_16x16x32_bf16 v[108:111], v[140:143], v[172:175], v[108:111]
	v_mfma_f32_16x16x32_bf16 v[92:95], v[116:119], v[180:183], v[92:95]
	v_mfma_f32_16x16x32_bf16 v[88:91], v[140:143], v[180:183], v[88:91]
	v_mfma_f32_16x16x32_bf16 v[76:79], v[116:119], v[204:207], v[76:79]
	v_mfma_f32_16x16x32_bf16 v[72:75], v[140:143], v[204:207], v[72:75]
	v_mfma_f32_16x16x32_bf16 v[124:127], v[144:147], v[160:163], v[124:127]
	v_mfma_f32_16x16x32_bf16 v[120:123], v[152:155], v[160:163], v[120:123]
	v_mfma_f32_16x16x32_bf16 v[100:103], v[144:147], v[168:171], v[100:103]
	v_mfma_f32_16x16x32_bf16 v[96:99], v[152:155], v[168:171], v[96:99]
	v_mfma_f32_16x16x32_bf16 v[84:87], v[144:147], v[176:179], v[84:87]
	v_mfma_f32_16x16x32_bf16 v[80:83], v[152:155], v[176:179], v[80:83]
	v_mfma_f32_16x16x32_bf16 v[68:71], v[144:147], v[200:203], v[68:71]
	v_mfma_f32_16x16x32_bf16 v[64:67], v[152:155], v[200:203], v[64:67]
	v_mfma_f32_16x16x32_bf16 v[124:127], v[148:151], v[164:167], v[124:127]
	v_mfma_f32_16x16x32_bf16 v[120:123], v[156:159], v[164:167], v[120:123]
	v_mfma_f32_16x16x32_bf16 v[100:103], v[148:151], v[172:175], v[100:103]
	v_mfma_f32_16x16x32_bf16 v[96:99], v[156:159], v[172:175], v[96:99]
	v_mfma_f32_16x16x32_bf16 v[84:87], v[148:151], v[180:183], v[84:87]
	v_mfma_f32_16x16x32_bf16 v[80:83], v[156:159], v[180:183], v[80:83]
	v_mfma_f32_16x16x32_bf16 v[68:71], v[148:151], v[204:207], v[68:71]
	v_mfma_f32_16x16x32_bf16 v[64:67], v[156:159], v[204:207], v[64:67]
	s_barrier
	s_add_i32 s50, s68, s9
	s_mov_b32 m0, s50
	s_add_u32 s98, s54, 0x80
	s_addc_u32 s99, s55, 0
	ds_read_b128 v[160:163], v223 offset:49152
	ds_read_b128 v[164:167], v223 offset:50176
	ds_read_b128 v[168:171], v223 offset:51200
	ds_read_b128 v[172:175], v223 offset:52224
	ds_read_b128 v[176:179], v223 offset:53248
	ds_read_b128 v[180:183], v223 offset:54272
	ds_read_b128 v[200:203], v223 offset:55296
	ds_read_b128 v[204:207], v223 offset:56320
	global_load_lds_dwordx4 v186, s[98:99]
	s_add_i32 m0, s50, 0x2000
	s_add_u32 s50, s54, 0x104080
	s_addc_u32 s51, s55, 0
	s_add_i32 s54, s69, s9
	global_load_lds_dwordx4 v190, s[98:99]
	s_mov_b32 m0, s54
	s_nop 0
	global_load_lds_dwordx4 v186, s[50:51]
	s_add_i32 m0, s54, 0x2000
	s_nop 0
	global_load_lds_dwordx4 v190, s[50:51]
	s_waitcnt vmcnt(4)
	s_waitcnt lgkmcnt(0)
	s_barrier
	v_mfma_f32_16x16x32_bf16 v[60:63], v[104:107], v[160:163], v[60:63]
	v_mfma_f32_16x16x32_bf16 v[56:59], v[128:131], v[160:163], v[56:59]
	v_mfma_f32_16x16x32_bf16 v[44:47], v[104:107], v[168:171], v[44:47]
	v_mfma_f32_16x16x32_bf16 v[40:43], v[128:131], v[168:171], v[40:43]
	v_mfma_f32_16x16x32_bf16 v[28:31], v[104:107], v[176:179], v[28:31]
	v_mfma_f32_16x16x32_bf16 v[24:27], v[128:131], v[176:179], v[24:27]
	v_mfma_f32_16x16x32_bf16 v[12:15], v[104:107], v[200:203], v[12:15]
	v_mfma_f32_16x16x32_bf16 v[8:11], v[128:131], v[200:203], v[8:11]
	v_mfma_f32_16x16x32_bf16 v[60:63], v[116:119], v[164:167], v[60:63]
	v_mfma_f32_16x16x32_bf16 v[56:59], v[140:143], v[164:167], v[56:59]
	v_mfma_f32_16x16x32_bf16 v[44:47], v[116:119], v[172:175], v[44:47]
	v_mfma_f32_16x16x32_bf16 v[40:43], v[140:143], v[172:175], v[40:43]
	v_mfma_f32_16x16x32_bf16 v[28:31], v[116:119], v[180:183], v[28:31]
	v_mfma_f32_16x16x32_bf16 v[24:27], v[140:143], v[180:183], v[24:27]
	v_mfma_f32_16x16x32_bf16 v[12:15], v[116:119], v[204:207], v[12:15]
	v_mfma_f32_16x16x32_bf16 v[8:11], v[140:143], v[204:207], v[8:11]
	v_mfma_f32_16x16x32_bf16 v[52:55], v[144:147], v[160:163], v[52:55]
	v_mfma_f32_16x16x32_bf16 v[48:51], v[152:155], v[160:163], v[48:51]
	v_mfma_f32_16x16x32_bf16 v[36:39], v[144:147], v[168:171], v[36:39]
	v_mfma_f32_16x16x32_bf16 v[32:35], v[152:155], v[168:171], v[32:35]
	v_mfma_f32_16x16x32_bf16 v[20:23], v[144:147], v[176:179], v[20:23]
	v_mfma_f32_16x16x32_bf16 v[16:19], v[152:155], v[176:179], v[16:19]
	v_mfma_f32_16x16x32_bf16 v[4:7], v[144:147], v[200:203], v[4:7]
	v_mfma_f32_16x16x32_bf16 v[0:3], v[152:155], v[200:203], v[0:3]
	v_mfma_f32_16x16x32_bf16 v[52:55], v[148:151], v[164:167], v[52:55]
	v_mfma_f32_16x16x32_bf16 v[48:51], v[156:159], v[164:167], v[48:51]
	v_mfma_f32_16x16x32_bf16 v[36:39], v[148:151], v[172:175], v[36:39]
	v_mfma_f32_16x16x32_bf16 v[32:35], v[156:159], v[172:175], v[32:35]
	v_mfma_f32_16x16x32_bf16 v[20:23], v[148:151], v[180:183], v[20:23]
	v_mfma_f32_16x16x32_bf16 v[16:19], v[156:159], v[180:183], v[16:19]
	v_mfma_f32_16x16x32_bf16 v[4:7], v[148:151], v[204:207], v[4:7]
	v_mfma_f32_16x16x32_bf16 v[0:3], v[156:159], v[204:207], v[0:3]
	s_barrier
	s_add_i32 s67, s67, 2
	s_add_u32 s65, s65, 0x100
	s_addc_u32 s66, s66, 0
	s_cmp_gt_u32 s67, 61
	s_mov_b64 s[50:51], s[52:53]
	s_cbranch_scc0 .LBB0_1037
	s_and_b64 vcc, exec, s[46:47]
	s_cbranch_vccz .LBB0_1040
	s_barrier

; #define PG8_STAGE(bufoff, gbase, voff) do { _Pragma("unroll") for (int _i = 0; _i < 2; ++_i) \
;         __builtin_amdgcn_global_load_lds((const unsigned*)((const char*)(gbase) + (voff)[_i]), (PG8_LAS unsigned*)(lds + (bufoff) + ldsw + _i * 8192), 16, 0, 0); } while (0)
; #define PG8_STAGE_NT(bufoff, gbase, voff) do { _Pragma("unroll") for (int _i = 0; _i < 2; ++_i) \
;         __builtin_amdgcn_global_load_lds((const unsigned*)((const char*)(gbase) + (voff)[_i]), (PG8_LAS unsigned*)(lds + (bufoff) + ldsw + _i * 8192), 16, 0, PG8_B_AUX); } while (0)
; #define PG8_LDA(dst, b, h) do { _Pragma("unroll") for (int m = 0; m < 4; ++m) _Pragma("unroll") for (int k = 0; k < 2; ++k) dst[m][k] = *(const PG8_LAS bf16x8*)(lds + PG8_SA(b, h) + aoff + m * 2048 + k * 1024); } while (0)
; #define PG8_LDB(dst, b, h) do { _Pragma("unroll") for (int n = 0; n < 2; ++n) _Pragma("unroll") for (int k = 0; k < 2; ++k) dst[n][k] = *(const PG8_LAS bf16x8*)(lds + PG8_SB(b, h) + boff + n * 2048 + k * 1024); } while (0)
; #define PG8_WAIT_V(n) asm volatile("s_waitcnt vmcnt(" #n ")" ::: "memory")
; #define PG8_WAIT_L(n) asm volatile("s_waitcnt lgkmcnt(" #n ")" ::: "memory")
; #define PG8_BAR __builtin_amdgcn_s_barrier()
; #define PG8_SCHED __builtin_amdgcn_sched_barrier(0)
; template <class Epi, class Sched, bool ALIGN_EPI = false, bool SP2 = false>
; __device__ __forceinline__ void gemm_phase(PG8_LAS unsigned char* lds, const Gemm g, const Sched& S, const Epi& E, int wid) {
;     ...
;             const bool last = (t == nt - 2);
;             const char* a1 = cA + (size_t)(t + 1) * kstep;
;             const char* a2 = last ? nA : cA + (size_t)(t + 2) * kstep; const char* b2 = last ? nB : cB + (size_t)(t + 2) * kstep;
;             const char* a3 = a2 + kstep; const char* b3 = b2 + kstep;
;             if (last && has_next) S.a_ready(nxt);
;             if constexpr (SP2) {
;             PG8_LDB(B0, 0, 0); PG8_LDB(B1, 0, 1); PG8_SCHED; PG8_LDA(At, 0, 0); PG8_STAGE(PG8_SA(1, 1), a1 + hstepA, voffA);
;             PG8_WAIT_V(8); PG8_WAIT_L(0); PG8_BAR; PG8_MMA(0, 0, At, B0); PG8_MMA(0, 1, At, B1); PG8_BAR; PG8_SCHED;
;             PG8_LDA(At, 0, 1); PG8_STAGE_NT(PG8_SB(0, 0), b2, voffB); PG8_STAGE_NT(PG8_SB(0, 1), b2 + hstepB, voffB); PG8_STAGE(PG8_SA(0, 0), a2, voffA);
;             PG8_WAIT_V(8); PG8_WAIT_L(0); PG8_BAR; PG8_MMA(1, 0, At, B0); PG8_MMA(1, 1, At, B1); PG8_BAR; PG8_SCHED;
.LBB0_1133:
	ds_read_b128 v[144:147], v155
	ds_read_b128 v[148:151], v155 offset:1024
	ds_read_b128 v[160:163], v155 offset:2048
	ds_read_b128 v[164:167], v155 offset:3072
	ds_read_b128 v[168:171], v156
	ds_read_b128 v[172:175], v156 offset:1024
	ds_read_b128 v[176:179], v156 offset:2048
	ds_read_b128 v[180:183], v156 offset:3072
	s_add_u32 s4, s46, 0x100
	s_addc_u32 s5, s47, 0
	s_add_u32 s98, s46, 0x80
	s_addc_u32 s99, s47, 0
	s_add_u32 s100, s46, 0x104080
	s_addc_u32 s101, s47, 0
	s_cmp_eq_u32 s63, 60
	s_cselect_b32 s51, s43, s5
	s_cselect_b32 s50, s42, s4
	s_cselect_b32 s49, s45, s62
	s_cselect_b32 s48, s44, s61
	s_add_i32 m0, s22, 0xc000
	ds_read_b128 v[184:187], v157
	ds_read_b128 v[188:191], v157 offset:1024
	ds_read_b128 v[192:195], v157 offset:2048
	ds_read_b128 v[196:199], v157 offset:3072
	ds_read_b128 v[200:203], v157 offset:4096
	ds_read_b128 v[204:207], v157 offset:5120
	ds_read_b128 v[208:211], v157 offset:6144
	ds_read_b128 v[212:215], v157 offset:7168
	global_load_lds_dwordx4 v134, s[100:101]
	s_add_i32 m0, s22, 0xe000
	s_nop 0
	global_load_lds_dwordx4 v130, s[100:101]
	s_mov_b32 m0, s52
	s_nop 0
	global_load_lds_dwordx4 v134, s[98:99]
	s_mov_b32 m0, s53
	s_nop 0
	global_load_lds_dwordx4 v130, s[98:99]
	s_waitcnt vmcnt(8)
	s_waitcnt lgkmcnt(0)
	s_barrier
	v_mfma_f32_16x16x32_bf16 v[112:115], v[144:147], v[184:187], v[112:115]
	v_mfma_f32_16x16x32_bf16 v[108:111], v[160:163], v[184:187], v[108:111]
	v_mfma_f32_16x16x32_bf16 v[104:107], v[144:147], v[192:195], v[104:107]
	v_mfma_f32_16x16x32_bf16 v[100:103], v[160:163], v[192:195], v[100:103]
	v_mfma_f32_16x16x32_bf16 v[92:95], v[144:147], v[200:203], v[92:95]
	v_mfma_f32_16x16x32_bf16 v[84:87], v[160:163], v[200:203], v[84:87]
	v_mfma_f32_16x16x32_bf16 v[76:79], v[144:147], v[208:211], v[76:79]
	v_mfma_f32_16x16x32_bf16 v[68:71], v[160:163], v[208:211], v[68:71]
	v_mfma_f32_16x16x32_bf16 v[112:115], v[148:151], v[188:191], v[112:115]
	v_mfma_f32_16x16x32_bf16 v[108:111], v[164:167], v[188:191], v[108:111]
	v_mfma_f32_16x16x32_bf16 v[104:107], v[148:151], v[196:199], v[104:107]
	v_mfma_f32_16x16x32_bf16 v[100:103], v[164:167], v[196:199], v[100:103]
	v_mfma_f32_16x16x32_bf16 v[92:95], v[148:151], v[204:207], v[92:95]
	v_mfma_f32_16x16x32_bf16 v[84:87], v[164:167], v[204:207], v[84:87]
	v_mfma_f32_16x16x32_bf16 v[76:79], v[148:151], v[212:215], v[76:79]
	v_mfma_f32_16x16x32_bf16 v[68:71], v[164:167], v[212:215], v[68:71]
	v_mfma_f32_16x16x32_bf16 v[124:127], v[168:171], v[184:187], v[124:127]
	v_mfma_f32_16x16x32_bf16 v[120:123], v[176:179], v[184:187], v[120:123]
	v_mfma_f32_16x16x32_bf16 v[116:119], v[168:171], v[192:195], v[116:119]
	v_mfma_f32_16x16x32_bf16 v[96:99], v[176:179], v[192:195], v[96:99]
	v_mfma_f32_16x16x32_bf16 v[88:91], v[168:171], v[200:203], v[88:91]
	v_mfma_f32_16x16x32_bf16 v[80:83], v[176:179], v[200:203], v[80:83]
	v_mfma_f32_16x16x32_bf16 v[72:75], v[168:171], v[208:211], v[72:75]
	v_mfma_f32_16x16x32_bf16 v[64:67], v[176:179], v[208:211], v[64:67]
	v_mfma_f32_16x16x32_bf16 v[124:127], v[172:175], v[188:191], v[124:127]
	v_mfma_f32_16x16x32_bf16 v[120:123], v[180:183], v[188:191], v[120:123]
	v_mfma_f32_16x16x32_bf16 v[116:119], v[172:175], v[196:199], v[116:119]
	v_mfma_f32_16x16x32_bf16 v[96:99], v[180:183], v[196:199], v[96:99]
	v_mfma_f32_16x16x32_bf16 v[88:91], v[172:175], v[204:207], v[88:91]
	v_mfma_f32_16x16x32_bf16 v[80:83], v[180:183], v[204:207], v[80:83]
	v_mfma_f32_16x16x32_bf16 v[72:75], v[172:175], v[212:215], v[72:75]
	v_mfma_f32_16x16x32_bf16 v[64:67], v[180:183], v[212:215], v[64:67]
	s_barrier
	s_add_i32 s46, s55, s9
	s_mov_b32 m0, s46
	ds_read_b128 v[184:187], v157 offset:16384
	ds_read_b128 v[188:191], v157 offset:17408
	ds_read_b128 v[192:195], v157 offset:18432
	ds_read_b128 v[196:199], v157 offset:19456
	ds_read_b128 v[200:203], v157 offset:20480
	ds_read_b128 v[204:207], v157 offset:21504
	ds_read_b128 v[208:211], v157 offset:22528
	ds_read_b128 v[212:215], v157 offset:23552
	global_load_lds_dwordx4 v132, s[48:49]
	s_add_i32 m0, s46, 0x2000
	s_add_u32 s46, s48, 0x104000
	s_addc_u32 s47, s49, 0
	s_add_i32 s64, s56, s9
	global_load_lds_dwordx4 v128, s[48:49]
	s_mov_b32 m0, s64
	s_nop 0
	global_load_lds_dwordx4 v132, s[46:47]
	s_add_i32 m0, s64, 0x2000
	s_nop 0
	global_load_lds_dwordx4 v128, s[46:47]
	s_waitcnt vmcnt(4)
	s_waitcnt lgkmcnt(0)
	s_barrier
	v_mfma_f32_16x16x32_bf16 v[60:63], v[144:147], v[184:187], v[60:63]
	v_mfma_f32_16x16x32_bf16 v[52:55], v[160:163], v[184:187], v[52:55]
	v_mfma_f32_16x16x32_bf16 v[44:47], v[144:147], v[192:195], v[44:47]
	v_mfma_f32_16x16x32_bf16 v[36:39], v[160:163], v[192:195], v[36:39]
	v_mfma_f32_16x16x32_bf16 v[28:31], v[144:147], v[200:203], v[28:31]
	v_mfma_f32_16x16x32_bf16 v[20:23], v[160:163], v[200:203], v[20:23]
	v_mfma_f32_16x16x32_bf16 v[12:15], v[144:147], v[208:211], v[12:15]
	v_mfma_f32_16x16x32_bf16 v[4:7], v[160:163], v[208:211], v[4:7]
	v_mfma_f32_16x16x32_bf16 v[60:63], v[148:151], v[188:191], v[60:63]
	v_mfma_f32_16x16x32_bf16 v[52:55], v[164:167], v[188:191], v[52:55]
	v_mfma_f32_16x16x32_bf16 v[44:47], v[148:151], v[196:199], v[44:47]
	v_mfma_f32_16x16x32_bf16 v[36:39], v[164:167], v[196:199], v[36:39]
	v_mfma_f32_16x16x32_bf16 v[28:31], v[148:151], v[204:207], v[28:31]
	v_mfma_f32_16x16x32_bf16 v[20:23], v[164:167], v[204:207], v[20:23]
	v_mfma_f32_16x16x32_bf16 v[12:15], v[148:151], v[212:215], v[12:15]
	v_mfma_f32_16x16x32_bf16 v[4:7], v[164:167], v[212:215], v[4:7]
	v_mfma_f32_16x16x32_bf16 v[56:59], v[168:171], v[184:187], v[56:59]
	v_mfma_f32_16x16x32_bf16 v[48:51], v[176:179], v[184:187], v[48:51]
	v_mfma_f32_16x16x32_bf16 v[40:43], v[168:171], v[192:195], v[40:43]
	v_mfma_f32_16x16x32_bf16 v[32:35], v[176:179], v[192:195], v[32:35]
	v_mfma_f32_16x16x32_bf16 v[24:27], v[168:171], v[200:203], v[24:27]
	v_mfma_f32_16x16x32_bf16 v[16:19], v[176:179], v[200:203], v[16:19]
	v_mfma_f32_16x16x32_bf16 v[8:11], v[168:171], v[208:211], v[8:11]
	v_mfma_f32_16x16x32_bf16 v[0:3], v[176:179], v[208:211], v[0:3]
	v_mfma_f32_16x16x32_bf16 v[56:59], v[172:175], v[188:191], v[56:59]
	v_mfma_f32_16x16x32_bf16 v[48:51], v[180:183], v[188:191], v[48:51]
	v_mfma_f32_16x16x32_bf16 v[40:43], v[172:175], v[196:199], v[40:43]
	v_mfma_f32_16x16x32_bf16 v[32:35], v[180:183], v[196:199], v[32:35]
	v_mfma_f32_16x16x32_bf16 v[24:27], v[172:175], v[204:207], v[24:27]
	v_mfma_f32_16x16x32_bf16 v[16:19], v[180:183], v[204:207], v[16:19]
	v_mfma_f32_16x16x32_bf16 v[8:11], v[172:175], v[212:215], v[8:11]
	v_mfma_f32_16x16x32_bf16 v[0:3], v[180:183], v[212:215], v[0:3]
	s_barrier
; #define PG8_STAGE(bufoff, gbase, voff) do { _Pragma("unroll") for (int _i = 0; _i < 2; ++_i) \
;         __builtin_amdgcn_global_load_lds((const unsigned*)((const char*)(gbase) + (voff)[_i]), (PG8_LAS unsigned*)(lds + (bufoff) + ldsw + _i * 8192), 16, 0, 0); } while (0)
; #define PG8_STAGE_NT(bufoff, gbase, voff) do { _Pragma("unroll") for (int _i = 0; _i < 2; ++_i) \
;         __builtin_amdgcn_global_load_lds((const unsigned*)((const char*)(gbase) + (voff)[_i]), (PG8_LAS unsigned*)(lds + (bufoff) + ldsw + _i * 8192), 16, 0, PG8_B_AUX); } while (0)
; #define PG8_LDA(dst, b, h) do { _Pragma("unroll") for (int m = 0; m < 4; ++m) _Pragma("unroll") for (int k = 0; k < 2; ++k) dst[m][k] = *(const PG8_LAS bf16x8*)(lds + PG8_SA(b, h) + aoff + m * 2048 + k * 1024); } while (0)
; #define PG8_LDB(dst, b, h) do { _Pragma("unroll") for (int n = 0; n < 2; ++n) _Pragma("unroll") for (int k = 0; k < 2; ++k) dst[n][k] = *(const PG8_LAS bf16x8*)(lds + PG8_SB(b, h) + boff + n * 2048 + k * 1024); } while (0)
; #define PG8_MMA(ai, bj, At, Bt) do { __builtin_amdgcn_s_setprio(1); _Pragma("unroll") for (int m = 0; m < 4; ++m) _Pragma("unroll") for (int n = 0; n < 2; ++n) _Pragma("unroll") for (int k = 0; k < 2; ++k) \
;         acc[ai][bj][m][n] = __builtin_amdgcn_mfma_f32_16x16x32_bf16(Bt[n][k], At[m][k], acc[ai][bj][m][n], 0, 0, 0); __builtin_amdgcn_s_setprio(0); } while (0)
; #define PG8_WAIT_V(n) asm volatile("s_waitcnt vmcnt(" #n ")" ::: "memory")
; #define PG8_WAIT_L(n) asm volatile("s_waitcnt lgkmcnt(" #n ")" ::: "memory")
; #define PG8_BAR __builtin_amdgcn_s_barrier()
; #define PG8_SCHED __builtin_amdgcn_sched_barrier(0)
; template <class Epi, class Sched, bool ALIGN_EPI = false, bool SP2 = false>
; __device__ __forceinline__ void gemm_phase(PG8_LAS unsigned char* lds, const Gemm g, const Sched& S, const Epi& E, int wid) {
;     ...
;             PG8_LDB(B0, 1, 0); PG8_LDB(B1, 1, 1); PG8_SCHED; PG8_LDA(At, 1, 0); PG8_STAGE(PG8_SA(0, 1), a2 + hstepA, voffA);
;             PG8_WAIT_V(8); PG8_WAIT_L(0); PG8_BAR; PG8_MMA(0, 0, At, B0); PG8_MMA(0, 1, At, B1); PG8_BAR; PG8_SCHED;
;             PG8_LDA(At, 1, 1); PG8_STAGE_NT(PG8_SB(1, 0), b3, voffB); PG8_STAGE_NT(PG8_SB(1, 1), b3 + hstepB, voffB); PG8_STAGE(PG8_SA(1, 0), a3, voffA);
;             PG8_WAIT_V(8); PG8_WAIT_L(0); PG8_BAR; PG8_MMA(1, 0, At, B0); PG8_MMA(1, 1, At, B1); PG8_BAR; PG8_SCHED;
	s_add_i32 s64, 0, 0x18000
	v_add_u32_e32 v159, s64, v153
	s_add_i32 s65, 0, 0x1c000
	ds_read_b128 v[144:147], v159
	ds_read_b128 v[148:151], v159 offset:1024
	ds_read_b128 v[160:163], v159 offset:2048
	ds_read_b128 v[164:167], v159 offset:3072
	v_add_u32_e32 v159, s65, v153
	ds_read_b128 v[168:171], v159
	ds_read_b128 v[172:175], v159 offset:1024
	ds_read_b128 v[176:179], v159 offset:2048
	ds_read_b128 v[180:183], v159 offset:3072
	s_add_u32 s46, s50, 0x104000
	s_addc_u32 s47, s51, 0
	s_mov_b32 m0, s24
	ds_read_b128 v[184:187], v157 offset:32768
	ds_read_b128 v[188:191], v157 offset:33792
	ds_read_b128 v[192:195], v157 offset:34816
	ds_read_b128 v[196:199], v157 offset:35840
	ds_read_b128 v[200:203], v157 offset:36864
	ds_read_b128 v[204:207], v157 offset:37888
	ds_read_b128 v[208:211], v157 offset:38912
	ds_read_b128 v[212:215], v157 offset:39936
	global_load_lds_dwordx4 v134, s[46:47]
	s_mov_b32 m0, s25
	s_nop 0
	global_load_lds_dwordx4 v130, s[46:47]
	s_mov_b32 m0, s22
	s_nop 0
	global_load_lds_dwordx4 v134, s[50:51]
	s_mov_b32 m0, s23
	s_nop 0
	global_load_lds_dwordx4 v130, s[50:51]
	s_waitcnt vmcnt(8)
	s_waitcnt lgkmcnt(0)
	s_barrier
	v_mfma_f32_16x16x32_bf16 v[112:115], v[144:147], v[184:187], v[112:115]
	v_mfma_f32_16x16x32_bf16 v[108:111], v[160:163], v[184:187], v[108:111]
	v_mfma_f32_16x16x32_bf16 v[104:107], v[144:147], v[192:195], v[104:107]
	v_mfma_f32_16x16x32_bf16 v[100:103], v[160:163], v[192:195], v[100:103]
	v_mfma_f32_16x16x32_bf16 v[92:95], v[144:147], v[200:203], v[92:95]
	v_mfma_f32_16x16x32_bf16 v[84:87], v[160:163], v[200:203], v[84:87]
	v_mfma_f32_16x16x32_bf16 v[76:79], v[144:147], v[208:211], v[76:79]
	v_mfma_f32_16x16x32_bf16 v[68:71], v[160:163], v[208:211], v[68:71]
	v_mfma_f32_16x16x32_bf16 v[112:115], v[148:151], v[188:191], v[112:115]
	v_mfma_f32_16x16x32_bf16 v[108:111], v[164:167], v[188:191], v[108:111]
	v_mfma_f32_16x16x32_bf16 v[104:107], v[148:151], v[196:199], v[104:107]
	v_mfma_f32_16x16x32_bf16 v[100:103], v[164:167], v[196:199], v[100:103]
	v_mfma_f32_16x16x32_bf16 v[92:95], v[148:151], v[204:207], v[92:95]
	v_mfma_f32_16x16x32_bf16 v[84:87], v[164:167], v[204:207], v[84:87]
	v_mfma_f32_16x16x32_bf16 v[76:79], v[148:151], v[212:215], v[76:79]
	v_mfma_f32_16x16x32_bf16 v[68:71], v[164:167], v[212:215], v[68:71]
	v_mfma_f32_16x16x32_bf16 v[124:127], v[168:171], v[184:187], v[124:127]
	v_mfma_f32_16x16x32_bf16 v[120:123], v[176:179], v[184:187], v[120:123]
	v_mfma_f32_16x16x32_bf16 v[116:119], v[168:171], v[192:195], v[116:119]
	v_mfma_f32_16x16x32_bf16 v[96:99], v[176:179], v[192:195], v[96:99]
	v_mfma_f32_16x16x32_bf16 v[88:91], v[168:171], v[200:203], v[88:91]
	v_mfma_f32_16x16x32_bf16 v[80:83], v[176:179], v[200:203], v[80:83]
	v_mfma_f32_16x16x32_bf16 v[72:75], v[168:171], v[208:211], v[72:75]
	v_mfma_f32_16x16x32_bf16 v[64:67], v[176:179], v[208:211], v[64:67]
	v_mfma_f32_16x16x32_bf16 v[124:127], v[172:175], v[188:191], v[124:127]
	v_mfma_f32_16x16x32_bf16 v[120:123], v[180:183], v[188:191], v[120:123]
	v_mfma_f32_16x16x32_bf16 v[116:119], v[172:175], v[196:199], v[116:119]
	v_mfma_f32_16x16x32_bf16 v[96:99], v[180:183], v[196:199], v[96:99]
	v_mfma_f32_16x16x32_bf16 v[88:91], v[172:175], v[204:207], v[88:91]
	v_mfma_f32_16x16x32_bf16 v[80:83], v[180:183], v[204:207], v[80:83]
	v_mfma_f32_16x16x32_bf16 v[72:75], v[172:175], v[212:215], v[72:75]
	v_mfma_f32_16x16x32_bf16 v[64:67], v[180:183], v[212:215], v[64:67]
	s_barrier
	s_add_i32 s46, s64, s9
	s_mov_b32 m0, s46
	s_add_u32 s98, s48, 0x80
	s_addc_u32 s99, s49, 0
	ds_read_b128 v[184:187], v157 offset:49152
	ds_read_b128 v[188:191], v157 offset:50176
	ds_read_b128 v[192:195], v157 offset:51200
	ds_read_b128 v[196:199], v157 offset:52224
	ds_read_b128 v[200:203], v157 offset:53248
	ds_read_b128 v[204:207], v157 offset:54272
	ds_read_b128 v[208:211], v157 offset:55296
	ds_read_b128 v[212:215], v157 offset:56320
	global_load_lds_dwordx4 v132, s[98:99]
	s_add_i32 m0, s46, 0x2000
	s_add_u32 s46, s48, 0x104080
	s_addc_u32 s47, s49, 0
	s_add_i32 s48, s65, s9
	global_load_lds_dwordx4 v128, s[98:99]
	s_mov_b32 m0, s48
	s_nop 0
	global_load_lds_dwordx4 v132, s[46:47]
	s_add_i32 m0, s48, 0x2000
	s_nop 0
	global_load_lds_dwordx4 v128, s[46:47]
	s_waitcnt vmcnt(4)
	s_waitcnt lgkmcnt(0)
	s_barrier
	v_mfma_f32_16x16x32_bf16 v[60:63], v[144:147], v[184:187], v[60:63]
	v_mfma_f32_16x16x32_bf16 v[52:55], v[160:163], v[184:187], v[52:55]
	v_mfma_f32_16x16x32_bf16 v[44:47], v[144:147], v[192:195], v[44:47]
	v_mfma_f32_16x16x32_bf16 v[36:39], v[160:163], v[192:195], v[36:39]
	v_mfma_f32_16x16x32_bf16 v[28:31], v[144:147], v[200:203], v[28:31]
	v_mfma_f32_16x16x32_bf16 v[20:23], v[160:163], v[200:203], v[20:23]
	v_mfma_f32_16x16x32_bf16 v[12:15], v[144:147], v[208:211], v[12:15]
	v_mfma_f32_16x16x32_bf16 v[4:7], v[160:163], v[208:211], v[4:7]
	v_mfma_f32_16x16x32_bf16 v[60:63], v[148:151], v[188:191], v[60:63]
	v_mfma_f32_16x16x32_bf16 v[52:55], v[164:167], v[188:191], v[52:55]
	v_mfma_f32_16x16x32_bf16 v[44:47], v[148:151], v[196:199], v[44:47]
	v_mfma_f32_16x16x32_bf16 v[36:39], v[164:167], v[196:199], v[36:39]
	v_mfma_f32_16x16x32_bf16 v[28:31], v[148:151], v[204:207], v[28:31]
	v_mfma_f32_16x16x32_bf16 v[20:23], v[164:167], v[204:207], v[20:23]
	v_mfma_f32_16x16x32_bf16 v[12:15], v[148:151], v[212:215], v[12:15]
	v_mfma_f32_16x16x32_bf16 v[4:7], v[164:167], v[212:215], v[4:7]
	v_mfma_f32_16x16x32_bf16 v[56:59], v[168:171], v[184:187], v[56:59]
	v_mfma_f32_16x16x32_bf16 v[48:51], v[176:179], v[184:187], v[48:51]
	v_mfma_f32_16x16x32_bf16 v[40:43], v[168:171], v[192:195], v[40:43]
	v_mfma_f32_16x16x32_bf16 v[32:35], v[176:179], v[192:195], v[32:35]
	v_mfma_f32_16x16x32_bf16 v[24:27], v[168:171], v[200:203], v[24:27]
	v_mfma_f32_16x16x32_bf16 v[16:19], v[176:179], v[200:203], v[16:19]
	v_mfma_f32_16x16x32_bf16 v[8:11], v[168:171], v[208:211], v[8:11]
	v_mfma_f32_16x16x32_bf16 v[0:3], v[176:179], v[208:211], v[0:3]
	v_mfma_f32_16x16x32_bf16 v[56:59], v[172:175], v[188:191], v[56:59]
	v_mfma_f32_16x16x32_bf16 v[48:51], v[180:183], v[188:191], v[48:51]
	v_mfma_f32_16x16x32_bf16 v[40:43], v[172:175], v[196:199], v[40:43]
	v_mfma_f32_16x16x32_bf16 v[32:35], v[180:183], v[196:199], v[32:35]
	v_mfma_f32_16x16x32_bf16 v[24:27], v[172:175], v[204:207], v[24:27]
	v_mfma_f32_16x16x32_bf16 v[16:19], v[180:183], v[204:207], v[16:19]
	v_mfma_f32_16x16x32_bf16 v[8:11], v[172:175], v[212:215], v[8:11]
	v_mfma_f32_16x16x32_bf16 v[0:3], v[180:183], v[212:215], v[0:3]
	s_barrier
	s_add_i32 s63, s63, 2
	s_add_u32 s61, s61, 0x100
	s_addc_u32 s62, s62, 0
	s_cmp_gt_u32 s63, 61
	s_mov_b64 s[46:47], s[4:5]
	s_cbranch_scc0 .LBB0_1133
	s_and_b64 vcc, exec, s[40:41]
	s_cbranch_vccz .LBB0_1136
	s_barrier

; #define PG8_STAGE(bufoff, gbase, voff) do { _Pragma("unroll") for (int _i = 0; _i < 2; ++_i) \
;         __builtin_amdgcn_global_load_lds((const unsigned*)((const char*)(gbase) + (voff)[_i]), (PG8_LAS unsigned*)(lds + (bufoff) + ldsw + _i * 8192), 16, 0, 0); } while (0)
; #define PG8_STAGE_NT(bufoff, gbase, voff) do { _Pragma("unroll") for (int _i = 0; _i < 2; ++_i) \
;         __builtin_amdgcn_global_load_lds((const unsigned*)((const char*)(gbase) + (voff)[_i]), (PG8_LAS unsigned*)(lds + (bufoff) + ldsw + _i * 8192), 16, 0, PG8_B_AUX); } while (0)
; #define PG8_LDA(dst, b, h) do { _Pragma("unroll") for (int m = 0; m < 4; ++m) _Pragma("unroll") for (int k = 0; k < 2; ++k) dst[m][k] = *(const PG8_LAS bf16x8*)(lds + PG8_SA(b, h) + aoff + m * 2048 + k * 1024); } while (0)
; #define PG8_LDB(dst, b, h) do { _Pragma("unroll") for (int n = 0; n < 2; ++n) _Pragma("unroll") for (int k = 0; k < 2; ++k) dst[n][k] = *(const PG8_LAS bf16x8*)(lds + PG8_SB(b, h) + boff + n * 2048 + k * 1024); } while (0)
; #define PG8_WAIT_V(n) asm volatile("s_waitcnt vmcnt(" #n ")" ::: "memory")
; #define PG8_WAIT_L(n) asm volatile("s_waitcnt lgkmcnt(" #n ")" ::: "memory")
; #define PG8_BAR __builtin_amdgcn_s_barrier()
; #define PG8_SCHED __builtin_amdgcn_sched_barrier(0)
; template <class Epi, class Sched, bool ALIGN_EPI = false, bool SP2 = false>
; __device__ __forceinline__ void gemm_phase(PG8_LAS unsigned char* lds, const Gemm g, const Sched& S, const Epi& E, int wid) {
;     ...
;             const bool last = (t == nt - 2);
;             const char* a1 = cA + (size_t)(t + 1) * kstep;
;             const char* a2 = last ? nA : cA + (size_t)(t + 2) * kstep; const char* b2 = last ? nB : cB + (size_t)(t + 2) * kstep;
;             const char* a3 = a2 + kstep; const char* b3 = b2 + kstep;
;             if (last && has_next) S.a_ready(nxt);
;             if constexpr (SP2) {
;             PG8_LDB(B0, 0, 0); PG8_LDB(B1, 0, 1); PG8_SCHED; PG8_LDA(At, 0, 0); PG8_STAGE(PG8_SA(1, 1), a1 + hstepA, voffA);
;             PG8_WAIT_V(8); PG8_WAIT_L(0); PG8_BAR; PG8_MMA(0, 0, At, B0); PG8_MMA(0, 1, At, B1); PG8_BAR; PG8_SCHED;
;             PG8_LDA(At, 0, 1); PG8_STAGE_NT(PG8_SB(0, 0), b2, voffB); PG8_STAGE_NT(PG8_SB(0, 1), b2 + hstepB, voffB); PG8_STAGE(PG8_SA(0, 0), a2, voffA);
;             PG8_WAIT_V(8); PG8_WAIT_L(0); PG8_BAR; PG8_MMA(1, 0, At, B0); PG8_MMA(1, 1, At, B1); PG8_BAR; PG8_SCHED;
.LBB0_1249:
	ds_read_b128 v[146:149], v141
	ds_read_b128 v[150:153], v141 offset:1024
	ds_read_b128 v[154:157], v141 offset:2048
	ds_read_b128 v[158:161], v141 offset:3072
	ds_read_b128 v[162:165], v142
	ds_read_b128 v[166:169], v142 offset:1024
	ds_read_b128 v[170:173], v142 offset:2048
	ds_read_b128 v[174:177], v142 offset:3072
	s_add_u32 s46, s14, s50
	s_addc_u32 s47, s15, s51
	s_add_u32 s53, s14, s44
	s_addc_u32 s54, s15, s45
	s_cmpk_eq_i32 s52, 0xa8
	s_cselect_b32 s49, s3, s47
	s_cselect_b32 s48, s2, s46
	s_cselect_b32 s47, s11, s54
	s_cselect_b32 s46, s10, s53
	s_mov_b32 m0, s57
	v_lshl_add_u64 v[212:213], s[14:15], 0, v[136:137]
	ds_read_b128 v[178:181], v143
	ds_read_b128 v[182:185], v143 offset:1024
	ds_read_b128 v[186:189], v143 offset:2048
	ds_read_b128 v[190:193], v143 offset:3072
	ds_read_b128 v[194:197], v143 offset:4096
	ds_read_b128 v[198:201], v143 offset:5120
	ds_read_b128 v[202:205], v143 offset:6144
	ds_read_b128 v[208:211], v143 offset:7168
	global_load_lds_dwordx4 v[212:213], off
	v_lshl_add_u64 v[212:213], s[14:15], 0, v[138:139]
	s_mov_b32 m0, s58
	s_nop 0
	global_load_lds_dwordx4 v[212:213], off
	s_sub_u32 s98, s14, 0x2b4000
	s_subb_u32 s99, s15, 0
	v_lshl_add_u64 v[212:213], s[98:99], 0, v[136:137]
	s_mov_b32 m0, s25
	s_nop 0
	global_load_lds_dwordx4 v[212:213], off
	v_lshl_add_u64 v[212:213], s[98:99], 0, v[138:139]
	s_mov_b32 m0, s56
	s_nop 0
	global_load_lds_dwordx4 v[212:213], off
	s_waitcnt vmcnt(8)
	s_waitcnt lgkmcnt(0)
	s_barrier
	v_mfma_f32_16x16x32_bf16 v[124:127], v[146:149], v[178:181], v[124:127]
	v_mfma_f32_16x16x32_bf16 v[120:123], v[154:157], v[178:181], v[120:123]
	v_mfma_f32_16x16x32_bf16 v[108:111], v[146:149], v[186:189], v[108:111]
	v_mfma_f32_16x16x32_bf16 v[104:107], v[154:157], v[186:189], v[104:107]
	v_mfma_f32_16x16x32_bf16 v[92:95], v[146:149], v[194:197], v[92:95]
	v_mfma_f32_16x16x32_bf16 v[88:91], v[154:157], v[194:197], v[88:91]
	v_mfma_f32_16x16x32_bf16 v[76:79], v[146:149], v[202:205], v[76:79]
	v_mfma_f32_16x16x32_bf16 v[72:75], v[154:157], v[202:205], v[72:75]
	v_mfma_f32_16x16x32_bf16 v[124:127], v[150:153], v[182:185], v[124:127]
	v_mfma_f32_16x16x32_bf16 v[120:123], v[158:161], v[182:185], v[120:123]
	v_mfma_f32_16x16x32_bf16 v[108:111], v[150:153], v[190:193], v[108:111]
	v_mfma_f32_16x16x32_bf16 v[104:107], v[158:161], v[190:193], v[104:107]
	v_mfma_f32_16x16x32_bf16 v[92:95], v[150:153], v[198:201], v[92:95]
	v_mfma_f32_16x16x32_bf16 v[88:91], v[158:161], v[198:201], v[88:91]
	v_mfma_f32_16x16x32_bf16 v[76:79], v[150:153], v[208:211], v[76:79]
	v_mfma_f32_16x16x32_bf16 v[72:75], v[158:161], v[208:211], v[72:75]
	v_mfma_f32_16x16x32_bf16 v[116:119], v[162:165], v[178:181], v[116:119]
	v_mfma_f32_16x16x32_bf16 v[112:115], v[170:173], v[178:181], v[112:115]
	v_mfma_f32_16x16x32_bf16 v[100:103], v[162:165], v[186:189], v[100:103]
	v_mfma_f32_16x16x32_bf16 v[96:99], v[170:173], v[186:189], v[96:99]
	v_mfma_f32_16x16x32_bf16 v[84:87], v[162:165], v[194:197], v[84:87]
	v_mfma_f32_16x16x32_bf16 v[80:83], v[170:173], v[194:197], v[80:83]
	v_mfma_f32_16x16x32_bf16 v[68:71], v[162:165], v[202:205], v[68:71]
	v_mfma_f32_16x16x32_bf16 v[64:67], v[170:173], v[202:205], v[64:67]
	v_mfma_f32_16x16x32_bf16 v[116:119], v[166:169], v[182:185], v[116:119]
	v_mfma_f32_16x16x32_bf16 v[112:115], v[174:177], v[182:185], v[112:115]
	v_mfma_f32_16x16x32_bf16 v[100:103], v[166:169], v[190:193], v[100:103]
	v_mfma_f32_16x16x32_bf16 v[96:99], v[174:177], v[190:193], v[96:99]
	v_mfma_f32_16x16x32_bf16 v[84:87], v[166:169], v[198:201], v[84:87]
	v_mfma_f32_16x16x32_bf16 v[80:83], v[174:177], v[198:201], v[80:83]
	v_mfma_f32_16x16x32_bf16 v[68:71], v[166:169], v[208:211], v[68:71]
	v_mfma_f32_16x16x32_bf16 v[64:67], v[174:177], v[208:211], v[64:67]
	s_barrier
	s_mov_b32 m0, s59
	v_lshl_add_u64 v[212:213], s[46:47], 0, v[130:131]
	s_add_u32 s54, s46, 0x2b4000
	ds_read_b128 v[178:181], v143 offset:16384
	ds_read_b128 v[182:185], v143 offset:17408
	ds_read_b128 v[186:189], v143 offset:18432
	ds_read_b128 v[190:193], v143 offset:19456
	ds_read_b128 v[194:197], v143 offset:20480
	ds_read_b128 v[198:201], v143 offset:21504
	ds_read_b128 v[202:205], v143 offset:22528
	ds_read_b128 v[208:211], v143 offset:23552
	global_load_lds_dwordx4 v[212:213], off
	v_lshl_add_u64 v[214:215], s[46:47], 0, v[134:135]
	s_mov_b32 m0, s60
	s_addc_u32 s55, s47, 0
	global_load_lds_dwordx4 v[214:215], off
	v_lshl_add_u64 v[216:217], s[54:55], 0, v[130:131]
	s_mov_b32 m0, s61
	global_load_lds_dwordx4 v[216:217], off
	v_lshl_add_u64 v[216:217], s[54:55], 0, v[134:135]
	s_mov_b32 m0, s62
	s_nop 0
	global_load_lds_dwordx4 v[216:217], off
	s_waitcnt vmcnt(4)
	s_waitcnt lgkmcnt(0)
	s_barrier
; #define PG8_STAGE(bufoff, gbase, voff) do { _Pragma("unroll") for (int _i = 0; _i < 2; ++_i) \
;         __builtin_amdgcn_global_load_lds((const unsigned*)((const char*)(gbase) + (voff)[_i]), (PG8_LAS unsigned*)(lds + (bufoff) + ldsw + _i * 8192), 16, 0, 0); } while (0)
; #define PG8_STAGE_NT(bufoff, gbase, voff) do { _Pragma("unroll") for (int _i = 0; _i < 2; ++_i) \
;         __builtin_amdgcn_global_load_lds((const unsigned*)((const char*)(gbase) + (voff)[_i]), (PG8_LAS unsigned*)(lds + (bufoff) + ldsw + _i * 8192), 16, 0, PG8_B_AUX); } while (0)
; #define PG8_LDA(dst, b, h) do { _Pragma("unroll") for (int m = 0; m < 4; ++m) _Pragma("unroll") for (int k = 0; k < 2; ++k) dst[m][k] = *(const PG8_LAS bf16x8*)(lds + PG8_SA(b, h) + aoff + m * 2048 + k * 1024); } while (0)
; #define PG8_LDB(dst, b, h) do { _Pragma("unroll") for (int n = 0; n < 2; ++n) _Pragma("unroll") for (int k = 0; k < 2; ++k) dst[n][k] = *(const PG8_LAS bf16x8*)(lds + PG8_SB(b, h) + boff + n * 2048 + k * 1024); } while (0)
; #define PG8_MMA(ai, bj, At, Bt) do { __builtin_amdgcn_s_setprio(1); _Pragma("unroll") for (int m = 0; m < 4; ++m) _Pragma("unroll") for (int n = 0; n < 2; ++n) _Pragma("unroll") for (int k = 0; k < 2; ++k) \
;         acc[ai][bj][m][n] = __builtin_amdgcn_mfma_f32_16x16x32_bf16(Bt[n][k], At[m][k], acc[ai][bj][m][n], 0, 0, 0); __builtin_amdgcn_s_setprio(0); } while (0)
; #define PG8_WAIT_V(n) asm volatile("s_waitcnt vmcnt(" #n ")" ::: "memory")
; #define PG8_WAIT_L(n) asm volatile("s_waitcnt lgkmcnt(" #n ")" ::: "memory")
; #define PG8_BAR __builtin_amdgcn_s_barrier()
; #define PG8_SCHED __builtin_amdgcn_sched_barrier(0)
; template <class Epi, class Sched, bool ALIGN_EPI = false, bool SP2 = false>
; __device__ __forceinline__ void gemm_phase(PG8_LAS unsigned char* lds, const Gemm g, const Sched& S, const Epi& E, int wid) {
;     ...
;             PG8_WAIT_V(8); PG8_WAIT_L(0); PG8_BAR; PG8_MMA(0, 0, At, B0); PG8_MMA(0, 1, At, B1); PG8_BAR; PG8_SCHED;
;             PG8_LDA(At, 0, 1); PG8_STAGE_NT(PG8_SB(0, 0), b2, voffB); PG8_STAGE_NT(PG8_SB(0, 1), b2 + hstepB, voffB); PG8_STAGE(PG8_SA(0, 0), a2, voffA);
;             PG8_WAIT_V(8); PG8_WAIT_L(0); PG8_BAR; PG8_MMA(1, 0, At, B0); PG8_MMA(1, 1, At, B1); PG8_BAR; PG8_SCHED;
;             PG8_LDB(B0, 1, 0); PG8_LDB(B1, 1, 1); PG8_SCHED; PG8_LDA(At, 1, 0); PG8_STAGE(PG8_SA(0, 1), a2 + hstepA, voffA);
	v_mfma_f32_16x16x32_bf16 v[60:63], v[146:149], v[178:181], v[60:63]
	v_mfma_f32_16x16x32_bf16 v[56:59], v[154:157], v[178:181], v[56:59]
	v_mfma_f32_16x16x32_bf16 v[44:47], v[146:149], v[186:189], v[44:47]
	v_mfma_f32_16x16x32_bf16 v[40:43], v[154:157], v[186:189], v[40:43]
	v_mfma_f32_16x16x32_bf16 v[28:31], v[146:149], v[194:197], v[28:31]
	v_mfma_f32_16x16x32_bf16 v[24:27], v[154:157], v[194:197], v[24:27]
	v_mfma_f32_16x16x32_bf16 v[12:15], v[146:149], v[202:205], v[12:15]
	v_mfma_f32_16x16x32_bf16 v[8:11], v[154:157], v[202:205], v[8:11]
	v_mfma_f32_16x16x32_bf16 v[60:63], v[150:153], v[182:185], v[60:63]
	v_mfma_f32_16x16x32_bf16 v[56:59], v[158:161], v[182:185], v[56:59]
	v_mfma_f32_16x16x32_bf16 v[44:47], v[150:153], v[190:193], v[44:47]
	v_mfma_f32_16x16x32_bf16 v[40:43], v[158:161], v[190:193], v[40:43]
	v_mfma_f32_16x16x32_bf16 v[28:31], v[150:153], v[198:201], v[28:31]
	v_mfma_f32_16x16x32_bf16 v[24:27], v[158:161], v[198:201], v[24:27]
	v_mfma_f32_16x16x32_bf16 v[12:15], v[150:153], v[208:211], v[12:15]
	v_mfma_f32_16x16x32_bf16 v[8:11], v[158:161], v[208:211], v[8:11]
	v_mfma_f32_16x16x32_bf16 v[52:55], v[162:165], v[178:181], v[52:55]
	v_mfma_f32_16x16x32_bf16 v[48:51], v[170:173], v[178:181], v[48:51]
	v_mfma_f32_16x16x32_bf16 v[36:39], v[162:165], v[186:189], v[36:39]
	v_mfma_f32_16x16x32_bf16 v[32:35], v[170:173], v[186:189], v[32:35]
	v_mfma_f32_16x16x32_bf16 v[20:23], v[162:165], v[194:197], v[20:23]
	v_mfma_f32_16x16x32_bf16 v[16:19], v[170:173], v[194:197], v[16:19]
	v_mfma_f32_16x16x32_bf16 v[4:7], v[162:165], v[202:205], v[4:7]
	v_mfma_f32_16x16x32_bf16 v[0:3], v[170:173], v[202:205], v[0:3]
	v_mfma_f32_16x16x32_bf16 v[52:55], v[166:169], v[182:185], v[52:55]
	v_mfma_f32_16x16x32_bf16 v[48:51], v[174:177], v[182:185], v[48:51]
	v_mfma_f32_16x16x32_bf16 v[36:39], v[166:169], v[190:193], v[36:39]
	v_mfma_f32_16x16x32_bf16 v[32:35], v[174:177], v[190:193], v[32:35]
	v_mfma_f32_16x16x32_bf16 v[20:23], v[166:169], v[198:201], v[20:23]
	v_mfma_f32_16x16x32_bf16 v[16:19], v[174:177], v[198:201], v[16:19]
	v_mfma_f32_16x16x32_bf16 v[4:7], v[166:169], v[208:211], v[4:7]
	v_mfma_f32_16x16x32_bf16 v[0:3], v[174:177], v[208:211], v[0:3]
	s_barrier
	ds_read_b128 v[146:149], v144
	ds_read_b128 v[150:153], v144 offset:1024
	ds_read_b128 v[154:157], v144 offset:2048
	ds_read_b128 v[158:161], v144 offset:3072
	ds_read_b128 v[162:165], v145
	ds_read_b128 v[166:169], v145 offset:1024
	ds_read_b128 v[170:173], v145 offset:2048
	ds_read_b128 v[174:177], v145 offset:3072
	v_lshl_add_u64 v[220:221], s[48:49], 0, v[128:129]
	s_mov_b32 m0, s17
	s_nop 0
	global_load_lds_dwordx4 v[220:221], off
	v_lshl_add_u64 v[220:221], s[48:49], 0, v[132:133]
	s_mov_b32 m0, s19
	s_nop 0
	global_load_lds_dwordx4 v[220:221], off
	s_add_u32 s48, s48, 0x2b4000
	s_addc_u32 s49, s49, 0
	s_mov_b32 m0, s22
	v_lshl_add_u64 v[220:221], s[48:49], 0, v[128:129]
	ds_read_b128 v[178:181], v143 offset:32768
	ds_read_b128 v[182:185], v143 offset:33792
	ds_read_b128 v[186:189], v143 offset:34816
	ds_read_b128 v[190:193], v143 offset:35840
	ds_read_b128 v[194:197], v143 offset:36864
	ds_read_b128 v[198:201], v143 offset:37888
	ds_read_b128 v[202:205], v143 offset:38912
	ds_read_b128 v[208:211], v143 offset:39936
	global_load_lds_dwordx4 v[220:221], off
	v_lshl_add_u64 v[220:221], s[48:49], 0, v[132:133]
	s_mov_b32 m0, s23
	s_nop 0
	global_load_lds_dwordx4 v[220:221], off
	s_waitcnt vmcnt(8)
	s_waitcnt lgkmcnt(0)
	s_barrier
	v_mfma_f32_16x16x32_bf16 v[124:127], v[146:149], v[178:181], v[124:127]
	v_mfma_f32_16x16x32_bf16 v[120:123], v[154:157], v[178:181], v[120:123]
	v_mfma_f32_16x16x32_bf16 v[108:111], v[146:149], v[186:189], v[108:111]
	v_mfma_f32_16x16x32_bf16 v[104:107], v[154:157], v[186:189], v[104:107]
	v_mfma_f32_16x16x32_bf16 v[92:95], v[146:149], v[194:197], v[92:95]
	v_mfma_f32_16x16x32_bf16 v[88:91], v[154:157], v[194:197], v[88:91]
	v_mfma_f32_16x16x32_bf16 v[76:79], v[146:149], v[202:205], v[76:79]
	v_mfma_f32_16x16x32_bf16 v[72:75], v[154:157], v[202:205], v[72:75]
	v_mfma_f32_16x16x32_bf16 v[124:127], v[150:153], v[182:185], v[124:127]
	v_mfma_f32_16x16x32_bf16 v[120:123], v[158:161], v[182:185], v[120:123]
	v_mfma_f32_16x16x32_bf16 v[108:111], v[150:153], v[190:193], v[108:111]
	v_mfma_f32_16x16x32_bf16 v[104:107], v[158:161], v[190:193], v[104:107]
	v_mfma_f32_16x16x32_bf16 v[92:95], v[150:153], v[198:201], v[92:95]
	v_mfma_f32_16x16x32_bf16 v[88:91], v[158:161], v[198:201], v[88:91]
	v_mfma_f32_16x16x32_bf16 v[76:79], v[150:153], v[208:211], v[76:79]
	v_mfma_f32_16x16x32_bf16 v[72:75], v[158:161], v[208:211], v[72:75]
	v_mfma_f32_16x16x32_bf16 v[116:119], v[162:165], v[178:181], v[116:119]
	v_mfma_f32_16x16x32_bf16 v[112:115], v[170:173], v[178:181], v[112:115]
	v_mfma_f32_16x16x32_bf16 v[100:103], v[162:165], v[186:189], v[100:103]
	v_mfma_f32_16x16x32_bf16 v[96:99], v[170:173], v[186:189], v[96:99]
	v_mfma_f32_16x16x32_bf16 v[84:87], v[162:165], v[194:197], v[84:87]
	v_mfma_f32_16x16x32_bf16 v[80:83], v[170:173], v[194:197], v[80:83]
	v_mfma_f32_16x16x32_bf16 v[68:71], v[162:165], v[202:205], v[68:71]
	v_mfma_f32_16x16x32_bf16 v[64:67], v[170:173], v[202:205], v[64:67]
	v_mfma_f32_16x16x32_bf16 v[116:119], v[166:169], v[182:185], v[116:119]
	v_mfma_f32_16x16x32_bf16 v[112:115], v[174:177], v[182:185], v[112:115]
	v_mfma_f32_16x16x32_bf16 v[100:103], v[166:169], v[190:193], v[100:103]
	v_mfma_f32_16x16x32_bf16 v[96:99], v[174:177], v[190:193], v[96:99]
	v_mfma_f32_16x16x32_bf16 v[84:87], v[166:169], v[198:201], v[84:87]
	v_mfma_f32_16x16x32_bf16 v[80:83], v[174:177], v[198:201], v[80:83]
	v_mfma_f32_16x16x32_bf16 v[68:71], v[166:169], v[208:211], v[68:71]
	v_mfma_f32_16x16x32_bf16 v[64:67], v[174:177], v[208:211], v[64:67]
	s_barrier
; #define PG8_STAGE(bufoff, gbase, voff) do { _Pragma("unroll") for (int _i = 0; _i < 2; ++_i) \
;         __builtin_amdgcn_global_load_lds((const unsigned*)((const char*)(gbase) + (voff)[_i]), (PG8_LAS unsigned*)(lds + (bufoff) + ldsw + _i * 8192), 16, 0, 0); } while (0)
; #define PG8_STAGE_NT(bufoff, gbase, voff) do { _Pragma("unroll") for (int _i = 0; _i < 2; ++_i) \
;         __builtin_amdgcn_global_load_lds((const unsigned*)((const char*)(gbase) + (voff)[_i]), (PG8_LAS unsigned*)(lds + (bufoff) + ldsw + _i * 8192), 16, 0, PG8_B_AUX); } while (0)
; #define PG8_LDA(dst, b, h) do { _Pragma("unroll") for (int m = 0; m < 4; ++m) _Pragma("unroll") for (int k = 0; k < 2; ++k) dst[m][k] = *(const PG8_LAS bf16x8*)(lds + PG8_SA(b, h) + aoff + m * 2048 + k * 1024); } while (0)
; #define PG8_MMA(ai, bj, At, Bt) do { __builtin_amdgcn_s_setprio(1); _Pragma("unroll") for (int m = 0; m < 4; ++m) _Pragma("unroll") for (int n = 0; n < 2; ++n) _Pragma("unroll") for (int k = 0; k < 2; ++k) \
;         acc[ai][bj][m][n] = __builtin_amdgcn_mfma_f32_16x16x32_bf16(Bt[n][k], At[m][k], acc[ai][bj][m][n], 0, 0, 0); __builtin_amdgcn_s_setprio(0); } while (0)
; #define PG8_WAIT_V(n) asm volatile("s_waitcnt vmcnt(" #n ")" ::: "memory")
; #define PG8_WAIT_L(n) asm volatile("s_waitcnt lgkmcnt(" #n ")" ::: "memory")
; #define PG8_BAR __builtin_amdgcn_s_barrier()
; #define PG8_SCHED __builtin_amdgcn_sched_barrier(0)
; template <class Epi, class Sched, bool ALIGN_EPI = false, bool SP2 = false>
; __device__ __forceinline__ void gemm_phase(PG8_LAS unsigned char* lds, const Gemm g, const Sched& S, const Epi& E, int wid) {
;     ...
;             PG8_LDA(At, 1, 1); PG8_STAGE_NT(PG8_SB(1, 0), b3, voffB); PG8_STAGE_NT(PG8_SB(1, 1), b3 + hstepB, voffB); PG8_STAGE(PG8_SA(1, 0), a3, voffA);
;             PG8_WAIT_V(8); PG8_WAIT_L(0); PG8_BAR; PG8_MMA(1, 0, At, B0); PG8_MMA(1, 1, At, B1); PG8_BAR; PG8_SCHED;
	s_mov_b32 m0, s63
	v_lshl_add_u64 v[212:213], v[212:213], 0, s[4:5]
	s_add_u32 s46, s46, 0x2b4080
	ds_read_b128 v[178:181], v143 offset:49152
	ds_read_b128 v[182:185], v143 offset:50176
	ds_read_b128 v[186:189], v143 offset:51200
	ds_read_b128 v[190:193], v143 offset:52224
	ds_read_b128 v[194:197], v143 offset:53248
	ds_read_b128 v[198:201], v143 offset:54272
	ds_read_b128 v[202:205], v143 offset:55296
	ds_read_b128 v[208:211], v143 offset:56320
	global_load_lds_dwordx4 v[212:213], off
	v_lshl_add_u64 v[212:213], v[214:215], 0, s[4:5]
	s_mov_b32 m0, s64
	s_addc_u32 s47, s47, 0
	global_load_lds_dwordx4 v[212:213], off
	v_lshl_add_u64 v[212:213], s[46:47], 0, v[130:131]
	s_mov_b32 m0, s65
	s_nop 0
	global_load_lds_dwordx4 v[212:213], off
	v_lshl_add_u64 v[212:213], s[46:47], 0, v[134:135]
	s_mov_b32 m0, s66
	s_nop 0
	global_load_lds_dwordx4 v[212:213], off
	s_waitcnt vmcnt(4)
	s_waitcnt lgkmcnt(0)
	s_barrier
	v_mfma_f32_16x16x32_bf16 v[60:63], v[146:149], v[178:181], v[60:63]
	v_mfma_f32_16x16x32_bf16 v[56:59], v[154:157], v[178:181], v[56:59]
	v_mfma_f32_16x16x32_bf16 v[44:47], v[146:149], v[186:189], v[44:47]
	v_mfma_f32_16x16x32_bf16 v[40:43], v[154:157], v[186:189], v[40:43]
	v_mfma_f32_16x16x32_bf16 v[28:31], v[146:149], v[194:197], v[28:31]
	v_mfma_f32_16x16x32_bf16 v[24:27], v[154:157], v[194:197], v[24:27]
	v_mfma_f32_16x16x32_bf16 v[12:15], v[146:149], v[202:205], v[12:15]
	v_mfma_f32_16x16x32_bf16 v[8:11], v[154:157], v[202:205], v[8:11]
	v_mfma_f32_16x16x32_bf16 v[60:63], v[150:153], v[182:185], v[60:63]
	v_mfma_f32_16x16x32_bf16 v[56:59], v[158:161], v[182:185], v[56:59]
	v_mfma_f32_16x16x32_bf16 v[44:47], v[150:153], v[190:193], v[44:47]
	v_mfma_f32_16x16x32_bf16 v[40:43], v[158:161], v[190:193], v[40:43]
	v_mfma_f32_16x16x32_bf16 v[28:31], v[150:153], v[198:201], v[28:31]
	v_mfma_f32_16x16x32_bf16 v[24:27], v[158:161], v[198:201], v[24:27]
	v_mfma_f32_16x16x32_bf16 v[12:15], v[150:153], v[208:211], v[12:15]
	v_mfma_f32_16x16x32_bf16 v[8:11], v[158:161], v[208:211], v[8:11]
	v_mfma_f32_16x16x32_bf16 v[52:55], v[162:165], v[178:181], v[52:55]
	v_mfma_f32_16x16x32_bf16 v[48:51], v[170:173], v[178:181], v[48:51]
	v_mfma_f32_16x16x32_bf16 v[36:39], v[162:165], v[186:189], v[36:39]
	v_mfma_f32_16x16x32_bf16 v[32:35], v[170:173], v[186:189], v[32:35]
	v_mfma_f32_16x16x32_bf16 v[20:23], v[162:165], v[194:197], v[20:23]
	v_mfma_f32_16x16x32_bf16 v[16:19], v[170:173], v[194:197], v[16:19]
	v_mfma_f32_16x16x32_bf16 v[4:7], v[162:165], v[202:205], v[4:7]
	v_mfma_f32_16x16x32_bf16 v[0:3], v[170:173], v[202:205], v[0:3]
	v_mfma_f32_16x16x32_bf16 v[52:55], v[166:169], v[182:185], v[52:55]
	v_mfma_f32_16x16x32_bf16 v[48:51], v[174:177], v[182:185], v[48:51]
	v_mfma_f32_16x16x32_bf16 v[36:39], v[166:169], v[190:193], v[36:39]
	v_mfma_f32_16x16x32_bf16 v[32:35], v[174:177], v[190:193], v[32:35]
	v_mfma_f32_16x16x32_bf16 v[20:23], v[166:169], v[198:201], v[20:23]
	v_mfma_f32_16x16x32_bf16 v[16:19], v[174:177], v[198:201], v[16:19]
	v_mfma_f32_16x16x32_bf16 v[4:7], v[166:169], v[208:211], v[4:7]
	v_mfma_f32_16x16x32_bf16 v[0:3], v[174:177], v[208:211], v[0:3]
	s_barrier
	s_add_i32 s52, s52, 2
	s_add_u32 s50, s50, 0x100
	s_addc_u32 s51, s51, 0
	s_add_u32 s44, s44, 0x100
	s_addc_u32 s45, s45, 0
	v_lshl_add_u64 v[136:137], v[136:137], 0, s[42:43]
	s_cmpk_lt_u32 s52, 0xaa
	v_lshl_add_u64 v[138:139], v[138:139], 0, s[42:43]
	s_cbranch_scc1 .LBB0_1249
	s_waitcnt vmcnt(0)
	s_cmpk_lt_u32 s95, 0x100
	s_cselect_b64 s[44:45], -1, 0
	s_cmpk_gt_u32 s95, 0xff
	s_cbranch_scc1 .LBB0_1252
	s_barrier

; #define PG8_STAGE(bufoff, gbase, voff) do { _Pragma("unroll") for (int _i = 0; _i < 2; ++_i) \
;         __builtin_amdgcn_global_load_lds((const unsigned*)((const char*)(gbase) + (voff)[_i]), (PG8_LAS unsigned*)(lds + (bufoff) + ldsw + _i * 8192), 16, 0, 0); } while (0)
; #define PG8_STAGE_NT(bufoff, gbase, voff) do { _Pragma("unroll") for (int _i = 0; _i < 2; ++_i) \
;         __builtin_amdgcn_global_load_lds((const unsigned*)((const char*)(gbase) + (voff)[_i]), (PG8_LAS unsigned*)(lds + (bufoff) + ldsw + _i * 8192), 16, 0, PG8_B_AUX); } while (0)
; #define PG8_LDA(dst, b, h) do { _Pragma("unroll") for (int m = 0; m < 4; ++m) _Pragma("unroll") for (int k = 0; k < 2; ++k) dst[m][k] = *(const PG8_LAS bf16x8*)(lds + PG8_SA(b, h) + aoff + m * 2048 + k * 1024); } while (0)
; #define PG8_LDB(dst, b, h) do { _Pragma("unroll") for (int n = 0; n < 2; ++n) _Pragma("unroll") for (int k = 0; k < 2; ++k) dst[n][k] = *(const PG8_LAS bf16x8*)(lds + PG8_SB(b, h) + boff + n * 2048 + k * 1024); } while (0)
; #define PG8_WAIT_V(n) asm volatile("s_waitcnt vmcnt(" #n ")" ::: "memory")
; #define PG8_WAIT_L(n) asm volatile("s_waitcnt lgkmcnt(" #n ")" ::: "memory")
; #define PG8_BAR __builtin_amdgcn_s_barrier()
; #define PG8_SCHED __builtin_amdgcn_sched_barrier(0)
; template <class Epi, class Sched, bool ALIGN_EPI = false, bool SP2 = false>
; __device__ __forceinline__ void gemm_phase(PG8_LAS unsigned char* lds, const Gemm g, const Sched& S, const Epi& E, int wid) {
;     ...
;             const bool last = (t == nt - 2);
;             const char* a1 = cA + (size_t)(t + 1) * kstep;
;             const char* a2 = last ? nA : cA + (size_t)(t + 2) * kstep; const char* b2 = last ? nB : cB + (size_t)(t + 2) * kstep;
;             const char* a3 = a2 + kstep; const char* b3 = b2 + kstep;
;             if (last && has_next) S.a_ready(nxt);
;             if constexpr (SP2) {
;             PG8_LDB(B0, 0, 0); PG8_LDB(B1, 0, 1); PG8_SCHED; PG8_LDA(At, 0, 0); PG8_STAGE(PG8_SA(1, 1), a1 + hstepA, voffA);
;             PG8_WAIT_V(8); PG8_WAIT_L(0); PG8_BAR; PG8_MMA(0, 0, At, B0); PG8_MMA(0, 1, At, B1); PG8_BAR; PG8_SCHED;
;             PG8_LDA(At, 0, 1); PG8_STAGE_NT(PG8_SB(0, 0), b2, voffB); PG8_STAGE_NT(PG8_SB(0, 1), b2 + hstepB, voffB); PG8_STAGE(PG8_SA(0, 0), a2, voffA);
;             PG8_WAIT_V(8); PG8_WAIT_L(0); PG8_BAR; PG8_MMA(1, 0, At, B0); PG8_MMA(1, 1, At, B1); PG8_BAR; PG8_SCHED;
.LBB0_1307:
	ds_read_b128 v[146:149], v141
	ds_read_b128 v[150:153], v141 offset:1024
	ds_read_b128 v[154:157], v141 offset:2048
	ds_read_b128 v[158:161], v141 offset:3072
	ds_read_b128 v[162:165], v142
	ds_read_b128 v[166:169], v142 offset:1024
	ds_read_b128 v[170:173], v142 offset:2048
	ds_read_b128 v[174:177], v142 offset:3072
	s_add_u32 s30, s14, s21
	s_addc_u32 s31, s15, s40
	s_add_u32 s48, s14, s8
	s_addc_u32 s49, s15, s9
	s_cmpk_eq_i32 s41, 0xa8
	s_cselect_b32 s39, s3, s31
	s_cselect_b32 s38, s2, s30
	s_cselect_b32 s31, s11, s49
	s_cselect_b32 s30, s10, s48
	s_mov_b32 m0, s57
	v_lshl_add_u64 v[202:203], s[14:15], 0, v[136:137]
	ds_read_b128 v[178:181], v143
	ds_read_b128 v[182:185], v143 offset:1024
	ds_read_b128 v[186:189], v143 offset:2048
	ds_read_b128 v[190:193], v143 offset:3072
	ds_read_b128 v[194:197], v143 offset:4096
	ds_read_b128 v[198:201], v143 offset:5120
	ds_read_b128 v[208:211], v143 offset:6144
	ds_read_b128 v[212:215], v143 offset:7168
	global_load_lds_dwordx4 v[202:203], off
	v_lshl_add_u64 v[202:203], s[14:15], 0, v[138:139]
	s_mov_b32 m0, s58
	s_nop 0
	global_load_lds_dwordx4 v[202:203], off
	s_sub_u32 s98, s14, 0x2b4000
	s_subb_u32 s99, s15, 0
	v_lshl_add_u64 v[202:203], s[98:99], 0, v[136:137]
	s_mov_b32 m0, s25
	s_nop 0
	global_load_lds_dwordx4 v[202:203], off
	v_lshl_add_u64 v[202:203], s[98:99], 0, v[138:139]
	s_mov_b32 m0, s56
	s_nop 0
	global_load_lds_dwordx4 v[202:203], off
	s_waitcnt vmcnt(8)
	s_waitcnt lgkmcnt(0)
	s_barrier
	v_mfma_f32_16x16x32_bf16 v[124:127], v[146:149], v[178:181], v[124:127]
	v_mfma_f32_16x16x32_bf16 v[120:123], v[154:157], v[178:181], v[120:123]
	v_mfma_f32_16x16x32_bf16 v[108:111], v[146:149], v[186:189], v[108:111]
	v_mfma_f32_16x16x32_bf16 v[104:107], v[154:157], v[186:189], v[104:107]
	v_mfma_f32_16x16x32_bf16 v[92:95], v[146:149], v[194:197], v[92:95]
	v_mfma_f32_16x16x32_bf16 v[88:91], v[154:157], v[194:197], v[88:91]
	v_mfma_f32_16x16x32_bf16 v[76:79], v[146:149], v[208:211], v[76:79]
	v_mfma_f32_16x16x32_bf16 v[72:75], v[154:157], v[208:211], v[72:75]
	v_mfma_f32_16x16x32_bf16 v[124:127], v[150:153], v[182:185], v[124:127]
	v_mfma_f32_16x16x32_bf16 v[120:123], v[158:161], v[182:185], v[120:123]
	v_mfma_f32_16x16x32_bf16 v[108:111], v[150:153], v[190:193], v[108:111]
	v_mfma_f32_16x16x32_bf16 v[104:107], v[158:161], v[190:193], v[104:107]
	v_mfma_f32_16x16x32_bf16 v[92:95], v[150:153], v[198:201], v[92:95]
	v_mfma_f32_16x16x32_bf16 v[88:91], v[158:161], v[198:201], v[88:91]
	v_mfma_f32_16x16x32_bf16 v[76:79], v[150:153], v[212:215], v[76:79]
	v_mfma_f32_16x16x32_bf16 v[72:75], v[158:161], v[212:215], v[72:75]
	v_mfma_f32_16x16x32_bf16 v[116:119], v[162:165], v[178:181], v[116:119]
	v_mfma_f32_16x16x32_bf16 v[112:115], v[170:173], v[178:181], v[112:115]
	v_mfma_f32_16x16x32_bf16 v[100:103], v[162:165], v[186:189], v[100:103]
	v_mfma_f32_16x16x32_bf16 v[96:99], v[170:173], v[186:189], v[96:99]
	v_mfma_f32_16x16x32_bf16 v[84:87], v[162:165], v[194:197], v[84:87]
	v_mfma_f32_16x16x32_bf16 v[80:83], v[170:173], v[194:197], v[80:83]
	v_mfma_f32_16x16x32_bf16 v[68:71], v[162:165], v[208:211], v[68:71]
	v_mfma_f32_16x16x32_bf16 v[64:67], v[170:173], v[208:211], v[64:67]
	v_mfma_f32_16x16x32_bf16 v[116:119], v[166:169], v[182:185], v[116:119]
	v_mfma_f32_16x16x32_bf16 v[112:115], v[174:177], v[182:185], v[112:115]
	v_mfma_f32_16x16x32_bf16 v[100:103], v[166:169], v[190:193], v[100:103]
	v_mfma_f32_16x16x32_bf16 v[96:99], v[174:177], v[190:193], v[96:99]
	v_mfma_f32_16x16x32_bf16 v[84:87], v[166:169], v[198:201], v[84:87]
	v_mfma_f32_16x16x32_bf16 v[80:83], v[174:177], v[198:201], v[80:83]
	v_mfma_f32_16x16x32_bf16 v[68:71], v[166:169], v[212:215], v[68:71]
	v_mfma_f32_16x16x32_bf16 v[64:67], v[174:177], v[212:215], v[64:67]
	s_barrier
	s_mov_b32 m0, s59
	v_lshl_add_u64 v[202:203], s[30:31], 0, v[130:131]
	s_add_u32 s48, s30, 0x2b4000
	ds_read_b128 v[178:181], v143 offset:16384
	ds_read_b128 v[182:185], v143 offset:17408
	ds_read_b128 v[186:189], v143 offset:18432
	ds_read_b128 v[190:193], v143 offset:19456
	ds_read_b128 v[194:197], v143 offset:20480
	ds_read_b128 v[198:201], v143 offset:21504
	ds_read_b128 v[208:211], v143 offset:22528
	ds_read_b128 v[212:215], v143 offset:23552
	global_load_lds_dwordx4 v[202:203], off
	v_lshl_add_u64 v[216:217], s[30:31], 0, v[134:135]
	s_mov_b32 m0, s60
	s_addc_u32 s49, s31, 0
	global_load_lds_dwordx4 v[216:217], off
	v_lshl_add_u64 v[218:219], s[48:49], 0, v[130:131]
	s_mov_b32 m0, s61
	global_load_lds_dwordx4 v[218:219], off
	v_lshl_add_u64 v[218:219], s[48:49], 0, v[134:135]
	s_mov_b32 m0, s62
	s_nop 0
	global_load_lds_dwordx4 v[218:219], off
	s_waitcnt vmcnt(4)
	s_waitcnt lgkmcnt(0)
	s_barrier
; #define PG8_STAGE(bufoff, gbase, voff) do { _Pragma("unroll") for (int _i = 0; _i < 2; ++_i) \
;         __builtin_amdgcn_global_load_lds((const unsigned*)((const char*)(gbase) + (voff)[_i]), (PG8_LAS unsigned*)(lds + (bufoff) + ldsw + _i * 8192), 16, 0, 0); } while (0)
; #define PG8_STAGE_NT(bufoff, gbase, voff) do { _Pragma("unroll") for (int _i = 0; _i < 2; ++_i) \
;         __builtin_amdgcn_global_load_lds((const unsigned*)((const char*)(gbase) + (voff)[_i]), (PG8_LAS unsigned*)(lds + (bufoff) + ldsw + _i * 8192), 16, 0, PG8_B_AUX); } while (0)
; #define PG8_LDA(dst, b, h) do { _Pragma("unroll") for (int m = 0; m < 4; ++m) _Pragma("unroll") for (int k = 0; k < 2; ++k) dst[m][k] = *(const PG8_LAS bf16x8*)(lds + PG8_SA(b, h) + aoff + m * 2048 + k * 1024); } while (0)
; #define PG8_LDB(dst, b, h) do { _Pragma("unroll") for (int n = 0; n < 2; ++n) _Pragma("unroll") for (int k = 0; k < 2; ++k) dst[n][k] = *(const PG8_LAS bf16x8*)(lds + PG8_SB(b, h) + boff + n * 2048 + k * 1024); } while (0)
; #define PG8_MMA(ai, bj, At, Bt) do { __builtin_amdgcn_s_setprio(1); _Pragma("unroll") for (int m = 0; m < 4; ++m) _Pragma("unroll") for (int n = 0; n < 2; ++n) _Pragma("unroll") for (int k = 0; k < 2; ++k) \
;         acc[ai][bj][m][n] = __builtin_amdgcn_mfma_f32_16x16x32_bf16(Bt[n][k], At[m][k], acc[ai][bj][m][n], 0, 0, 0); __builtin_amdgcn_s_setprio(0); } while (0)
; #define PG8_WAIT_V(n) asm volatile("s_waitcnt vmcnt(" #n ")" ::: "memory")
; #define PG8_WAIT_L(n) asm volatile("s_waitcnt lgkmcnt(" #n ")" ::: "memory")
; #define PG8_BAR __builtin_amdgcn_s_barrier()
; #define PG8_SCHED __builtin_amdgcn_sched_barrier(0)
; template <class Epi, class Sched, bool ALIGN_EPI = false, bool SP2 = false>
; __device__ __forceinline__ void gemm_phase(PG8_LAS unsigned char* lds, const Gemm g, const Sched& S, const Epi& E, int wid) {
;     ...
;             PG8_WAIT_V(8); PG8_WAIT_L(0); PG8_BAR; PG8_MMA(0, 0, At, B0); PG8_MMA(0, 1, At, B1); PG8_BAR; PG8_SCHED;
;             PG8_LDA(At, 0, 1); PG8_STAGE_NT(PG8_SB(0, 0), b2, voffB); PG8_STAGE_NT(PG8_SB(0, 1), b2 + hstepB, voffB); PG8_STAGE(PG8_SA(0, 0), a2, voffA);
;             PG8_WAIT_V(8); PG8_WAIT_L(0); PG8_BAR; PG8_MMA(1, 0, At, B0); PG8_MMA(1, 1, At, B1); PG8_BAR; PG8_SCHED;
;             PG8_LDB(B0, 1, 0); PG8_LDB(B1, 1, 1); PG8_SCHED; PG8_LDA(At, 1, 0); PG8_STAGE(PG8_SA(0, 1), a2 + hstepA, voffA);
	v_mfma_f32_16x16x32_bf16 v[60:63], v[146:149], v[178:181], v[60:63]
	v_mfma_f32_16x16x32_bf16 v[56:59], v[154:157], v[178:181], v[56:59]
	v_mfma_f32_16x16x32_bf16 v[44:47], v[146:149], v[186:189], v[44:47]
	v_mfma_f32_16x16x32_bf16 v[40:43], v[154:157], v[186:189], v[40:43]
	v_mfma_f32_16x16x32_bf16 v[28:31], v[146:149], v[194:197], v[28:31]
	v_mfma_f32_16x16x32_bf16 v[24:27], v[154:157], v[194:197], v[24:27]
	v_mfma_f32_16x16x32_bf16 v[12:15], v[146:149], v[208:211], v[12:15]
	v_mfma_f32_16x16x32_bf16 v[8:11], v[154:157], v[208:211], v[8:11]
	v_mfma_f32_16x16x32_bf16 v[60:63], v[150:153], v[182:185], v[60:63]
	v_mfma_f32_16x16x32_bf16 v[56:59], v[158:161], v[182:185], v[56:59]
	v_mfma_f32_16x16x32_bf16 v[44:47], v[150:153], v[190:193], v[44:47]
	v_mfma_f32_16x16x32_bf16 v[40:43], v[158:161], v[190:193], v[40:43]
	v_mfma_f32_16x16x32_bf16 v[28:31], v[150:153], v[198:201], v[28:31]
	v_mfma_f32_16x16x32_bf16 v[24:27], v[158:161], v[198:201], v[24:27]
	v_mfma_f32_16x16x32_bf16 v[12:15], v[150:153], v[212:215], v[12:15]
	v_mfma_f32_16x16x32_bf16 v[8:11], v[158:161], v[212:215], v[8:11]
	v_mfma_f32_16x16x32_bf16 v[52:55], v[162:165], v[178:181], v[52:55]
	v_mfma_f32_16x16x32_bf16 v[48:51], v[170:173], v[178:181], v[48:51]
	v_mfma_f32_16x16x32_bf16 v[36:39], v[162:165], v[186:189], v[36:39]
	v_mfma_f32_16x16x32_bf16 v[32:35], v[170:173], v[186:189], v[32:35]
	v_mfma_f32_16x16x32_bf16 v[20:23], v[162:165], v[194:197], v[20:23]
	v_mfma_f32_16x16x32_bf16 v[16:19], v[170:173], v[194:197], v[16:19]
	v_mfma_f32_16x16x32_bf16 v[4:7], v[162:165], v[208:211], v[4:7]
	v_mfma_f32_16x16x32_bf16 v[0:3], v[170:173], v[208:211], v[0:3]
	v_mfma_f32_16x16x32_bf16 v[52:55], v[166:169], v[182:185], v[52:55]
	v_mfma_f32_16x16x32_bf16 v[48:51], v[174:177], v[182:185], v[48:51]
	v_mfma_f32_16x16x32_bf16 v[36:39], v[166:169], v[190:193], v[36:39]
	v_mfma_f32_16x16x32_bf16 v[32:35], v[174:177], v[190:193], v[32:35]
	v_mfma_f32_16x16x32_bf16 v[20:23], v[166:169], v[198:201], v[20:23]
	v_mfma_f32_16x16x32_bf16 v[16:19], v[174:177], v[198:201], v[16:19]
	v_mfma_f32_16x16x32_bf16 v[4:7], v[166:169], v[212:215], v[4:7]
	v_mfma_f32_16x16x32_bf16 v[0:3], v[174:177], v[212:215], v[0:3]
	s_barrier
	ds_read_b128 v[146:149], v144
	ds_read_b128 v[150:153], v144 offset:1024
	ds_read_b128 v[154:157], v144 offset:2048
	ds_read_b128 v[158:161], v144 offset:3072
	ds_read_b128 v[162:165], v145
	ds_read_b128 v[166:169], v145 offset:1024
	ds_read_b128 v[170:173], v145 offset:2048
	ds_read_b128 v[174:177], v145 offset:3072
	v_lshl_add_u64 v[222:223], s[38:39], 0, v[128:129]
	s_mov_b32 m0, s17
	s_nop 0
	global_load_lds_dwordx4 v[222:223], off
	v_lshl_add_u64 v[222:223], s[38:39], 0, v[132:133]
	s_mov_b32 m0, s19
	s_nop 0
	global_load_lds_dwordx4 v[222:223], off
	s_add_u32 s38, s38, 0x2b4000
	s_addc_u32 s39, s39, 0
	s_mov_b32 m0, s22
	v_lshl_add_u64 v[222:223], s[38:39], 0, v[128:129]
	ds_read_b128 v[178:181], v143 offset:32768
	ds_read_b128 v[182:185], v143 offset:33792
	ds_read_b128 v[186:189], v143 offset:34816
	ds_read_b128 v[190:193], v143 offset:35840
	ds_read_b128 v[194:197], v143 offset:36864
	ds_read_b128 v[198:201], v143 offset:37888
	ds_read_b128 v[208:211], v143 offset:38912
	ds_read_b128 v[212:215], v143 offset:39936
	global_load_lds_dwordx4 v[222:223], off
	v_lshl_add_u64 v[222:223], s[38:39], 0, v[132:133]
	s_mov_b32 m0, s23
	s_nop 0
	global_load_lds_dwordx4 v[222:223], off
	s_waitcnt vmcnt(8)
	s_waitcnt lgkmcnt(0)
	s_barrier
	v_mfma_f32_16x16x32_bf16 v[124:127], v[146:149], v[178:181], v[124:127]
	v_mfma_f32_16x16x32_bf16 v[120:123], v[154:157], v[178:181], v[120:123]
	v_mfma_f32_16x16x32_bf16 v[108:111], v[146:149], v[186:189], v[108:111]
	v_mfma_f32_16x16x32_bf16 v[104:107], v[154:157], v[186:189], v[104:107]
	v_mfma_f32_16x16x32_bf16 v[92:95], v[146:149], v[194:197], v[92:95]
	v_mfma_f32_16x16x32_bf16 v[88:91], v[154:157], v[194:197], v[88:91]
	v_mfma_f32_16x16x32_bf16 v[76:79], v[146:149], v[208:211], v[76:79]
	v_mfma_f32_16x16x32_bf16 v[72:75], v[154:157], v[208:211], v[72:75]
	v_mfma_f32_16x16x32_bf16 v[124:127], v[150:153], v[182:185], v[124:127]
	v_mfma_f32_16x16x32_bf16 v[120:123], v[158:161], v[182:185], v[120:123]
	v_mfma_f32_16x16x32_bf16 v[108:111], v[150:153], v[190:193], v[108:111]
	v_mfma_f32_16x16x32_bf16 v[104:107], v[158:161], v[190:193], v[104:107]
	v_mfma_f32_16x16x32_bf16 v[92:95], v[150:153], v[198:201], v[92:95]
	v_mfma_f32_16x16x32_bf16 v[88:91], v[158:161], v[198:201], v[88:91]
	v_mfma_f32_16x16x32_bf16 v[76:79], v[150:153], v[212:215], v[76:79]
	v_mfma_f32_16x16x32_bf16 v[72:75], v[158:161], v[212:215], v[72:75]
	v_mfma_f32_16x16x32_bf16 v[116:119], v[162:165], v[178:181], v[116:119]
	v_mfma_f32_16x16x32_bf16 v[112:115], v[170:173], v[178:181], v[112:115]
	v_mfma_f32_16x16x32_bf16 v[100:103], v[162:165], v[186:189], v[100:103]
	v_mfma_f32_16x16x32_bf16 v[96:99], v[170:173], v[186:189], v[96:99]
	v_mfma_f32_16x16x32_bf16 v[84:87], v[162:165], v[194:197], v[84:87]
	v_mfma_f32_16x16x32_bf16 v[80:83], v[170:173], v[194:197], v[80:83]
	v_mfma_f32_16x16x32_bf16 v[68:71], v[162:165], v[208:211], v[68:71]
	v_mfma_f32_16x16x32_bf16 v[64:67], v[170:173], v[208:211], v[64:67]
	v_mfma_f32_16x16x32_bf16 v[116:119], v[166:169], v[182:185], v[116:119]
	v_mfma_f32_16x16x32_bf16 v[112:115], v[174:177], v[182:185], v[112:115]
	v_mfma_f32_16x16x32_bf16 v[100:103], v[166:169], v[190:193], v[100:103]
	v_mfma_f32_16x16x32_bf16 v[96:99], v[174:177], v[190:193], v[96:99]
	v_mfma_f32_16x16x32_bf16 v[84:87], v[166:169], v[198:201], v[84:87]
	v_mfma_f32_16x16x32_bf16 v[80:83], v[174:177], v[198:201], v[80:83]
	v_mfma_f32_16x16x32_bf16 v[68:71], v[166:169], v[212:215], v[68:71]
	v_mfma_f32_16x16x32_bf16 v[64:67], v[174:177], v[212:215], v[64:67]
	s_barrier
; #define PG8_STAGE(bufoff, gbase, voff) do { _Pragma("unroll") for (int _i = 0; _i < 2; ++_i) \
;         __builtin_amdgcn_global_load_lds((const unsigned*)((const char*)(gbase) + (voff)[_i]), (PG8_LAS unsigned*)(lds + (bufoff) + ldsw + _i * 8192), 16, 0, 0); } while (0)
; #define PG8_STAGE_NT(bufoff, gbase, voff) do { _Pragma("unroll") for (int _i = 0; _i < 2; ++_i) \
;         __builtin_amdgcn_global_load_lds((const unsigned*)((const char*)(gbase) + (voff)[_i]), (PG8_LAS unsigned*)(lds + (bufoff) + ldsw + _i * 8192), 16, 0, PG8_B_AUX); } while (0)
; #define PG8_LDA(dst, b, h) do { _Pragma("unroll") for (int m = 0; m < 4; ++m) _Pragma("unroll") for (int k = 0; k < 2; ++k) dst[m][k] = *(const PG8_LAS bf16x8*)(lds + PG8_SA(b, h) + aoff + m * 2048 + k * 1024); } while (0)
; #define PG8_MMA(ai, bj, At, Bt) do { __builtin_amdgcn_s_setprio(1); _Pragma("unroll") for (int m = 0; m < 4; ++m) _Pragma("unroll") for (int n = 0; n < 2; ++n) _Pragma("unroll") for (int k = 0; k < 2; ++k) \
;         acc[ai][bj][m][n] = __builtin_amdgcn_mfma_f32_16x16x32_bf16(Bt[n][k], At[m][k], acc[ai][bj][m][n], 0, 0, 0); __builtin_amdgcn_s_setprio(0); } while (0)
; #define PG8_WAIT_V(n) asm volatile("s_waitcnt vmcnt(" #n ")" ::: "memory")
; #define PG8_WAIT_L(n) asm volatile("s_waitcnt lgkmcnt(" #n ")" ::: "memory")
; #define PG8_BAR __builtin_amdgcn_s_barrier()
; #define PG8_SCHED __builtin_amdgcn_sched_barrier(0)
; template <class Epi, class Sched, bool ALIGN_EPI = false, bool SP2 = false>
; __device__ __forceinline__ void gemm_phase(PG8_LAS unsigned char* lds, const Gemm g, const Sched& S, const Epi& E, int wid) {
;     ...
;             PG8_LDA(At, 1, 1); PG8_STAGE_NT(PG8_SB(1, 0), b3, voffB); PG8_STAGE_NT(PG8_SB(1, 1), b3 + hstepB, voffB); PG8_STAGE(PG8_SA(1, 0), a3, voffA);
;             PG8_WAIT_V(8); PG8_WAIT_L(0); PG8_BAR; PG8_MMA(1, 0, At, B0); PG8_MMA(1, 1, At, B1); PG8_BAR; PG8_SCHED;
	s_mov_b32 m0, s63
	v_lshl_add_u64 v[202:203], v[202:203], 0, s[4:5]
	s_add_u32 s30, s30, 0x2b4080
	ds_read_b128 v[178:181], v143 offset:49152
	ds_read_b128 v[182:185], v143 offset:50176
	ds_read_b128 v[186:189], v143 offset:51200
	ds_read_b128 v[190:193], v143 offset:52224
	ds_read_b128 v[194:197], v143 offset:53248
	ds_read_b128 v[198:201], v143 offset:54272
	ds_read_b128 v[208:211], v143 offset:55296
	ds_read_b128 v[212:215], v143 offset:56320
	global_load_lds_dwordx4 v[202:203], off
	v_lshl_add_u64 v[202:203], v[216:217], 0, s[4:5]
	s_mov_b32 m0, s64
	s_addc_u32 s31, s31, 0
	global_load_lds_dwordx4 v[202:203], off
	v_lshl_add_u64 v[202:203], s[30:31], 0, v[130:131]
	s_mov_b32 m0, s65
	s_nop 0
	global_load_lds_dwordx4 v[202:203], off
	v_lshl_add_u64 v[202:203], s[30:31], 0, v[134:135]
	s_mov_b32 m0, s66
	s_nop 0
	global_load_lds_dwordx4 v[202:203], off
	s_waitcnt vmcnt(4)
	s_waitcnt lgkmcnt(0)
	s_barrier
	v_mfma_f32_16x16x32_bf16 v[60:63], v[146:149], v[178:181], v[60:63]
	v_mfma_f32_16x16x32_bf16 v[56:59], v[154:157], v[178:181], v[56:59]
	v_mfma_f32_16x16x32_bf16 v[44:47], v[146:149], v[186:189], v[44:47]
	v_mfma_f32_16x16x32_bf16 v[40:43], v[154:157], v[186:189], v[40:43]
	v_mfma_f32_16x16x32_bf16 v[28:31], v[146:149], v[194:197], v[28:31]
	v_mfma_f32_16x16x32_bf16 v[24:27], v[154:157], v[194:197], v[24:27]
	v_mfma_f32_16x16x32_bf16 v[12:15], v[146:149], v[208:211], v[12:15]
	v_mfma_f32_16x16x32_bf16 v[8:11], v[154:157], v[208:211], v[8:11]
	v_mfma_f32_16x16x32_bf16 v[60:63], v[150:153], v[182:185], v[60:63]
	v_mfma_f32_16x16x32_bf16 v[56:59], v[158:161], v[182:185], v[56:59]
	v_mfma_f32_16x16x32_bf16 v[44:47], v[150:153], v[190:193], v[44:47]
	v_mfma_f32_16x16x32_bf16 v[40:43], v[158:161], v[190:193], v[40:43]
	v_mfma_f32_16x16x32_bf16 v[28:31], v[150:153], v[198:201], v[28:31]
	v_mfma_f32_16x16x32_bf16 v[24:27], v[158:161], v[198:201], v[24:27]
	v_mfma_f32_16x16x32_bf16 v[12:15], v[150:153], v[212:215], v[12:15]
	v_mfma_f32_16x16x32_bf16 v[8:11], v[158:161], v[212:215], v[8:11]
	v_mfma_f32_16x16x32_bf16 v[52:55], v[162:165], v[178:181], v[52:55]
	v_mfma_f32_16x16x32_bf16 v[48:51], v[170:173], v[178:181], v[48:51]
	v_mfma_f32_16x16x32_bf16 v[36:39], v[162:165], v[186:189], v[36:39]
	v_mfma_f32_16x16x32_bf16 v[32:35], v[170:173], v[186:189], v[32:35]
	v_mfma_f32_16x16x32_bf16 v[20:23], v[162:165], v[194:197], v[20:23]
	v_mfma_f32_16x16x32_bf16 v[16:19], v[170:173], v[194:197], v[16:19]
	v_mfma_f32_16x16x32_bf16 v[4:7], v[162:165], v[208:211], v[4:7]
	v_mfma_f32_16x16x32_bf16 v[0:3], v[170:173], v[208:211], v[0:3]
	v_mfma_f32_16x16x32_bf16 v[52:55], v[166:169], v[182:185], v[52:55]
	v_mfma_f32_16x16x32_bf16 v[48:51], v[174:177], v[182:185], v[48:51]
	v_mfma_f32_16x16x32_bf16 v[36:39], v[166:169], v[190:193], v[36:39]
	v_mfma_f32_16x16x32_bf16 v[32:35], v[174:177], v[190:193], v[32:35]
	v_mfma_f32_16x16x32_bf16 v[20:23], v[166:169], v[198:201], v[20:23]
	v_mfma_f32_16x16x32_bf16 v[16:19], v[174:177], v[198:201], v[16:19]
	v_mfma_f32_16x16x32_bf16 v[4:7], v[166:169], v[212:215], v[4:7]
	v_mfma_f32_16x16x32_bf16 v[0:3], v[174:177], v[212:215], v[0:3]
	s_barrier
	s_add_i32 s41, s41, 2
	s_add_u32 s21, s21, 0x100
	s_addc_u32 s40, s40, 0
	s_add_u32 s8, s8, 0x100
	s_addc_u32 s9, s9, 0
	v_lshl_add_u64 v[136:137], v[136:137], 0, s[28:29]
	s_cmpk_lt_u32 s41, 0xaa
	v_lshl_add_u64 v[138:139], v[138:139], 0, s[28:29]
	s_cbranch_scc1 .LBB0_1307
	s_waitcnt vmcnt(0)
	s_andn2_b64 vcc, exec, s[44:45]
	s_cbranch_vccnz .LBB0_1310
	s_barrier
